# v15qkprio
# baseline (speedup 1.0000x reference)
; __device__ __forceinline__ void finishSM(f32x16& p0, f32x16& p1, float alpha, float& l_reg, bf16x8& pa0, bf16x8& pa1, bf16x8& pa2, bf16x8& pa3) {
; #pragma unroll
;     for (int r = 0; r < 16; ++r) p1[r] = __builtin_amdgcn_exp2f(p1[r]);
;     float ps = 0;
; #pragma unroll
;     for (int r = 0; r < 16; ++r) ps += p0[r];
; #pragma unroll
;     for (int r = 0; r < 16; ++r) ps += p1[r];
;     { auto rr = __builtin_amdgcn_permlane32_swap(__float_as_uint(ps), __float_as_uint(ps), false, false);
;       ps = __uint_as_float(rr[0]) + __uint_as_float(rr[1]); }
;     l_reg = l_reg * alpha + ps;
;     PK4(p0, 0, pa0); PK4(p0, 8, pa1); PK4(p1, 0, pa2); PK4(p1, 8, pa3);
; }
; __device__ __forceinline__ void pv_tile(f32x16* o, int vb0, bf16x8 pa0, bf16x8 pa1, bf16x8 pa2, bf16x8 pa3) {
;     ...
;     PV_D0(0); PV_D0(1); PV_D0(2); PV_D0(3);
;     ...
; }
.LBB0_323:
	s_setprio 0
	v_add_f32_e32 v2, 0, v243
	v_add_f32_e32 v2, v242, v2
	v_add_f32_e32 v2, v241, v2
	v_add_f32_e32 v2, v240, v2
	v_add_f32_e32 v2, v239, v2
	v_add_f32_e32 v2, v238, v2
	v_add_f32_e32 v2, v237, v2
	v_add_f32_e32 v2, v236, v2
	v_add_f32_e32 v2, v235, v2
	v_add_f32_e32 v2, v234, v2
	v_add_f32_e32 v2, v233, v2
	v_add_f32_e32 v2, v232, v2
	v_exp_f32_e32 v10, v14
	v_add_f32_e32 v2, v231, v2
	v_exp_f32_e32 v11, v15
	v_add_f32_e32 v2, v230, v2
	v_exp_f32_e32 v12, v176
	v_add_f32_e32 v2, v216, v2
	v_exp_f32_e32 v13, v177
	v_add_f32_e32 v2, v179, v2
	v_exp_f32_e32 v14, v116
	v_add_f32_e32 v2, v10, v2
	v_exp_f32_e32 v15, v117
	v_add_f32_e32 v2, v11, v2
	v_exp_f32_e32 v80, v118
	v_add_f32_e32 v2, v12, v2
	v_exp_f32_e32 v81, v119
	v_add_f32_e32 v2, v13, v2
	v_exp_f32_e32 v82, v120
	v_add_f32_e32 v2, v14, v2
	v_exp_f32_e32 v83, v121
	v_add_f32_e32 v2, v15, v2
	v_exp_f32_e32 v84, v122
	v_add_f32_e32 v2, v80, v2
	v_exp_f32_e32 v85, v123
	v_add_f32_e32 v2, v81, v2
	v_exp_f32_e32 v86, v124
	v_add_f32_e32 v2, v82, v2
	v_exp_f32_e32 v87, v125
	v_add_f32_e32 v2, v83, v2
	v_exp_f32_e32 v88, v126
	v_add_f32_e32 v2, v84, v2
	v_exp_f32_e32 v89, v127
	v_add_f32_e32 v2, v85, v2
	v_add_f32_e32 v2, v86, v2
	v_add_f32_e32 v2, v87, v2
	v_add_f32_e32 v2, v88, v2
	v_add_f32_e32 v2, v89, v2
	v_mov_b32_e32 v3, v2
	s_nop 1
	v_permlane32_swap_b32_e32 v2, v3
	v_add_f32_e32 v2, v2, v3
	s_add_i32 s0, 0, 0xc000
	v_add_f32_e32 v0, v0, v2
	v_cvt_pk_bf16_f32 v2, v243, v242
	v_cvt_pk_bf16_f32 v3, v241, v240
	v_cvt_pk_bf16_f32 v4, v239, v238
	v_cvt_pk_bf16_f32 v5, v237, v236
	v_cvt_pk_bf16_f32 v6, v235, v234
	v_cvt_pk_bf16_f32 v7, v233, v232
	v_cvt_pk_bf16_f32 v8, v231, v230
	v_cvt_pk_bf16_f32 v9, v216, v179
	v_cvt_pk_bf16_f32 v10, v10, v11
	v_cvt_pk_bf16_f32 v11, v12, v13
	v_cvt_pk_bf16_f32 v12, v14, v15
	v_cvt_pk_bf16_f32 v13, v80, v81
	v_cvt_pk_bf16_f32 v80, v82, v83
	v_cvt_pk_bf16_f32 v81, v84, v85
	v_cvt_pk_bf16_f32 v82, v86, v87
	v_cvt_pk_bf16_f32 v83, v88, v89
	v_add_u32_e32 v14, s0, v218
	ds_read_b64_tr_b16 v[84:85], v14 offset:0
	ds_read_b64_tr_b16 v[86:87], v14 offset:0x800
	ds_read_b64_tr_b16 v[88:89], v14 offset:0x1000
	ds_read_b64_tr_b16 v[90:91], v14 offset:0x1800
	ds_read_b64_tr_b16 v[92:93], v14 offset:0x2000
	ds_read_b64_tr_b16 v[94:95], v14 offset:0x2800
	ds_read_b64_tr_b16 v[96:97], v14 offset:0x3000
	ds_read_b64_tr_b16 v[98:99], v14 offset:0x3800
	s_waitcnt lgkmcnt(0)
	v_mfma_f32_32x32x16_bf16 v[64:79], v[84:87], v[2:5], v[64:79]
	ds_read_b64_tr_b16 v[84:85], v14 offset:0x200
	ds_read_b64_tr_b16 v[86:87], v14 offset:0xa00
	v_mfma_f32_32x32x16_bf16 v[64:79], v[88:91], v[6:9], v[64:79]
	ds_read_b64_tr_b16 v[88:89], v14 offset:0x1200
	ds_read_b64_tr_b16 v[90:91], v14 offset:0x1a00
	s_mov_b32 s49, s81
	v_ashrrev_i32_e32 v181, 31, v180
	s_xor_b64 s[82:83], s[96:97], -1
	v_mfma_f32_32x32x16_bf16 v[64:79], v[92:95], v[10:13], v[64:79]
	ds_read_b64_tr_b16 v[92:93], v14 offset:0x2200
	ds_read_b64_tr_b16 v[94:95], v14 offset:0x2a00
	s_mov_b64 s[96:97], 0
	v_mfma_f32_32x32x16_bf16 v[64:79], v[96:99], v[80:83], v[64:79]
	ds_read_b64_tr_b16 v[96:97], v14 offset:0x3200
	ds_read_b64_tr_b16 v[98:99], v14 offset:0x3a00
	s_nop 0
	s_waitcnt lgkmcnt(0)
	s_nop 0
	v_mfma_f32_32x32x16_bf16 v[48:63], v[84:87], v[2:5], v[48:63]
	ds_read_b64_tr_b16 v[84:85], v14 offset:0x400
	ds_read_b64_tr_b16 v[86:87], v14 offset:0xc00
	v_mfma_f32_32x32x16_bf16 v[48:63], v[88:91], v[6:9], v[48:63]
	ds_read_b64_tr_b16 v[88:89], v14 offset:0x1400
	ds_read_b64_tr_b16 v[90:91], v14 offset:0x1c00
	v_mfma_f32_32x32x16_bf16 v[48:63], v[92:95], v[10:13], v[48:63]
	ds_read_b64_tr_b16 v[92:93], v14 offset:0x2400
	ds_read_b64_tr_b16 v[94:95], v14 offset:0x2c00
	v_mfma_f32_32x32x16_bf16 v[48:63], v[96:99], v[80:83], v[48:63]
	ds_read_b64_tr_b16 v[96:97], v14 offset:0x3400
	ds_read_b64_tr_b16 v[98:99], v14 offset:0x3c00
	s_nop 0
	s_waitcnt lgkmcnt(0)
	s_nop 0
	v_mfma_f32_32x32x16_bf16 v[32:47], v[84:87], v[2:5], v[32:47]
	ds_read_b64_tr_b16 v[84:85], v14 offset:0x600
	ds_read_b64_tr_b16 v[86:87], v14 offset:0xe00
	v_mfma_f32_32x32x16_bf16 v[32:47], v[88:91], v[6:9], v[32:47]
	ds_read_b64_tr_b16 v[88:89], v14 offset:0x1600
	ds_read_b64_tr_b16 v[90:91], v14 offset:0x1e00
	v_mfma_f32_32x32x16_bf16 v[32:47], v[92:95], v[10:13], v[32:47]
	ds_read_b64_tr_b16 v[92:93], v14 offset:0x2600
	ds_read_b64_tr_b16 v[94:95], v14 offset:0x2e00
	v_mfma_f32_32x32x16_bf16 v[32:47], v[96:99], v[80:83], v[32:47]
	ds_read_b64_tr_b16 v[96:97], v14 offset:0x3600
	ds_read_b64_tr_b16 v[98:99], v14 offset:0x3e00
	s_nop 0
	s_waitcnt lgkmcnt(0)
	s_barrier
; __device__ __forceinline__ float bf_lo(unsigned w) { return __uint_as_float(w << 16); }
; __device__ __forceinline__ float bf_hi(unsigned w) { return __uint_as_float(w & 0xffff0000u); }
; __device__ __forceinline__ float siluf_(float v) { return v * sigmoidf_(v); }
; __device__ __forceinline__ void attn_block(const Params& p, LAS unsigned char* lds, int h, int qb) {
;     ...
;     { finishSM(pB0, pB1, alB, l_reg, pa0, pa1, pa2, pa3); pv_tile(o, vb0 + ((ntiles - 1) & 3) * SHM_V, pa0, pa1, pa2, pa3); }
;     __syncthreads();
;     ...
;     const float il = __builtin_amdgcn_rcpf(l_reg);
;     const bf16_t* zp = proj + (size_t)qrow * NP + C_ZA + h * 128; unsigned char* ya8 = p.ws + O_YA8;
; #pragma unroll
;     for (int d0 = 0; d0 < 4; ++d0)
; #pragma unroll
;         for (int rq = 0; rq < 4; ++rq) { const int dv = d0 * 32 + 8 * rq + 4 * hi; const u32x2 zz = *(const u32x2*)(zp + dv);
;             const float y0 = o[d0][rq * 4 + 0] * il * siluf_(bf_lo(zz.x)), y1 = o[d0][rq * 4 + 1] * il * siluf_(bf_hi(zz.x));
;             const float y2 = o[d0][rq * 4 + 2] * il * siluf_(bf_lo(zz.y)), y3 = o[d0][rq * 4 + 3] * il * siluf_(bf_hi(zz.y));
;             int x8 = __builtin_amdgcn_cvt_pk_fp8_f32(y0 * 64.f, y1 * 64.f, 0, false); x8 = __builtin_amdgcn_cvt_pk_fp8_f32(y2 * 64.f, y3 * 64.f, x8, true);
;             *(int*)(ya8 + (size_t)qrow * 1024 + h * 128 + dv) = x8; }
	v_mfma_f32_32x32x16_bf16 v[16:31], v[84:87], v[2:5], v[16:31]
	v_mov_b64_e32 v[2:3], s[14:15]
	v_mad_i64_i32 v[2:3], s[0:1], v180, s31, v[2:3]
	v_lshl_add_u64 v[2:3], v[2:3], 0, s[48:49]
	s_mov_b64 s[0:1], 0xe200880
	v_lshlrev_b64 v[4:5], 10, v[180:181]
	v_lshl_add_u64 v[4:5], s[64:65], 0, v[4:5]
	v_mfma_f32_32x32x16_bf16 v[16:31], v[88:91], v[6:9], v[16:31]
	v_lshlrev_b32_e32 v6, 3, v193
	v_mov_b32_e32 v7, v1
	v_lshl_add_u64 v[6:7], v[2:3], 0, v[6:7]
	v_lshl_add_u64 v[2:3], v[6:7], 0, s[0:1]
	global_load_dwordx2 v[128:129], v[2:3], off offset:0
	global_load_dwordx2 v[130:131], v[2:3], off offset:16
	global_load_dwordx2 v[132:133], v[2:3], off offset:32
	global_load_dwordx2 v[134:135], v[2:3], off offset:48
	global_load_dwordx2 v[136:137], v[2:3], off offset:64
	global_load_dwordx2 v[138:139], v[2:3], off offset:80
	global_load_dwordx2 v[140:141], v[2:3], off offset:96
	global_load_dwordx2 v[142:143], v[2:3], off offset:112
	global_load_dwordx2 v[144:145], v[2:3], off offset:128
	global_load_dwordx2 v[146:147], v[2:3], off offset:144
	global_load_dwordx2 v[148:149], v[2:3], off offset:160
	global_load_dwordx2 v[150:151], v[2:3], off offset:176
	global_load_dwordx2 v[152:153], v[2:3], off offset:192
	global_load_dwordx2 v[154:155], v[2:3], off offset:208
	global_load_dwordx2 v[156:157], v[2:3], off offset:224
	global_load_dwordx2 v[158:159], v[2:3], off offset:240
	s_mov_b32 s0, 0xe200000
	v_add_co_u32_e32 v6, vcc, s0, v6
	v_mfma_f32_32x32x16_bf16 v[16:31], v[92:95], v[10:13], v[16:31]
	s_nop 0
	v_addc_co_u32_e32 v7, vcc, 0, v7, vcc
	v_rcp_f32_e32 v8, v0
	v_lshlrev_b32_e32 v0, 2, v193
	v_lshl_add_u64 v[4:5], v[4:5], 0, v[0:1]
	s_and_b64 vcc, exec, s[82:83]
	v_mul_f32_e32 v9, v8, v64
	v_mul_f32_e32 v0, v8, v68
	v_mfma_f32_32x32x16_bf16 v[16:31], v[96:99], v[80:83], v[16:31]
	s_waitcnt vmcnt(15)
	v_mov_b32_e32 v6, v128
	v_mov_b32_e32 v7, v129
	v_lshlrev_b32_e32 v10, 16, v6
	v_mul_f32_e32 v11, 0xbfb8aa3b, v10
	v_exp_f32_e32 v11, v11
	v_and_b32_e32 v6, 0xffff0000, v6
	v_add_f32_e32 v11, 1.0, v11
	v_rcp_f32_e32 v11, v11
	s_nop 0
	v_mul_f32_e32 v10, v11, v10
	v_mul_f32_e32 v11, 0xbfb8aa3b, v6
	v_exp_f32_e32 v11, v11
	v_mul_f32_e32 v9, v9, v10
	v_mul_f32_e32 v10, v8, v65
	v_mul_f32_e32 v9, 0x42800000, v9
	v_add_f32_e32 v11, 1.0, v11
	v_rcp_f32_e32 v11, v11
	s_nop 0
	v_mul_f32_e32 v6, v11, v6
	v_lshlrev_b32_e32 v11, 16, v7
	v_mul_f32_e32 v12, 0xbfb8aa3b, v11
	v_exp_f32_e32 v12, v12
	v_and_b32_e32 v7, 0xffff0000, v7
	v_mul_f32_e32 v6, v10, v6
	v_mul_f32_e32 v10, v8, v66
	v_add_f32_e32 v12, 1.0, v12
	v_rcp_f32_e32 v12, v12
	v_mul_f32_e32 v6, 0x42800000, v6
	v_mul_f32_e32 v11, v12, v11
	v_mul_f32_e32 v12, 0xbfb8aa3b, v7
	v_exp_f32_e32 v12, v12
	v_mul_f32_e32 v10, v10, v11
	v_mul_f32_e32 v11, v8, v67
	v_add_f32_e32 v12, 1.0, v12
	v_rcp_f32_e32 v12, v12
	s_nop 0
	v_mul_f32_e32 v7, v12, v7
	v_mul_f32_e32 v7, v11, v7
	v_mov_b32_e32 v11, v1
	v_cvt_pk_fp8_f32 v11, v9, v6
	v_mul_f32_e32 v6, 0x42800000, v10
	v_mul_f32_e32 v7, 0x42800000, v7
	v_cvt_pk_fp8_f32 v11, v6, v7 op_sel:[0,0,1]
	global_store_dword v[4:5], v11, off
	s_waitcnt vmcnt(15)
	v_mov_b32_e32 v6, v130
	v_mov_b32_e32 v7, v131
	v_lshlrev_b32_e32 v9, 16, v6
	v_mul_f32_e32 v10, 0xbfb8aa3b, v9
	v_exp_f32_e32 v10, v10
	v_and_b32_e32 v6, 0xffff0000, v6
	v_add_f32_e32 v10, 1.0, v10
	v_rcp_f32_e32 v10, v10
	s_nop 0
	v_mul_f32_e32 v9, v10, v9
	v_mul_f32_e32 v10, 0xbfb8aa3b, v6
	v_exp_f32_e32 v10, v10
	v_mul_f32_e32 v0, v0, v9
	v_mul_f32_e32 v9, v8, v69
	v_mul_f32_e32 v0, 0x42800000, v0
	v_add_f32_e32 v10, 1.0, v10
	v_rcp_f32_e32 v10, v10
	s_nop 0
	v_mul_f32_e32 v6, v10, v6
	v_lshlrev_b32_e32 v10, 16, v7
	v_mul_f32_e32 v11, 0xbfb8aa3b, v10
	v_exp_f32_e32 v11, v11
	v_and_b32_e32 v7, 0xffff0000, v7
	v_mul_f32_e32 v6, v9, v6
	v_mul_f32_e32 v9, v8, v70
	v_add_f32_e32 v11, 1.0, v11
	v_rcp_f32_e32 v11, v11
	v_mul_f32_e32 v6, 0x42800000, v6
	v_mul_f32_e32 v10, v11, v10
	v_mul_f32_e32 v11, 0xbfb8aa3b, v7
	v_exp_f32_e32 v11, v11
	v_mul_f32_e32 v9, v9, v10
	v_mul_f32_e32 v10, v8, v71
	v_add_f32_e32 v11, 1.0, v11
	v_rcp_f32_e32 v11, v11
	s_nop 0
	v_mul_f32_e32 v7, v11, v7
	v_mul_f32_e32 v7, v10, v7
	v_mov_b32_e32 v10, v1
	v_cvt_pk_fp8_f32 v10, v0, v6
	v_mul_f32_e32 v0, 0x42800000, v9
	v_mul_f32_e32 v6, 0x42800000, v7
	v_cvt_pk_fp8_f32 v10, v0, v6 op_sel:[0,0,1]
	v_mul_f32_e32 v0, v8, v72
	global_store_dword v[4:5], v10, off offset:8
	s_waitcnt vmcnt(15)
	v_mov_b32_e32 v6, v132
	v_mov_b32_e32 v7, v133
	v_lshlrev_b32_e32 v9, 16, v6
	v_mul_f32_e32 v10, 0xbfb8aa3b, v9
	v_exp_f32_e32 v10, v10
	v_and_b32_e32 v6, 0xffff0000, v6
	v_add_f32_e32 v10, 1.0, v10
	v_rcp_f32_e32 v10, v10
	s_nop 0
	v_mul_f32_e32 v9, v10, v9
	v_mul_f32_e32 v10, 0xbfb8aa3b, v6
	v_exp_f32_e32 v10, v10
	v_mul_f32_e32 v0, v0, v9
	v_mul_f32_e32 v9, v8, v73
	v_mul_f32_e32 v0, 0x42800000, v0
	v_add_f32_e32 v10, 1.0, v10
	v_rcp_f32_e32 v10, v10
	s_nop 0
	v_mul_f32_e32 v6, v10, v6
	v_lshlrev_b32_e32 v10, 16, v7
	v_mul_f32_e32 v11, 0xbfb8aa3b, v10
	v_exp_f32_e32 v11, v11
	v_and_b32_e32 v7, 0xffff0000, v7
	v_mul_f32_e32 v6, v9, v6
	v_mul_f32_e32 v9, v8, v74
	v_add_f32_e32 v11, 1.0, v11
	v_rcp_f32_e32 v11, v11
	v_mul_f32_e32 v6, 0x42800000, v6
	v_mul_f32_e32 v10, v11, v10
	v_mul_f32_e32 v11, 0xbfb8aa3b, v7
	v_exp_f32_e32 v11, v11
	v_mul_f32_e32 v9, v9, v10
	v_mul_f32_e32 v10, v8, v75
	v_add_f32_e32 v11, 1.0, v11
	v_rcp_f32_e32 v11, v11
	s_nop 0
	v_mul_f32_e32 v7, v11, v7
	v_mul_f32_e32 v7, v10, v7
	v_mov_b32_e32 v10, v1
	v_cvt_pk_fp8_f32 v10, v0, v6
	v_mul_f32_e32 v0, 0x42800000, v9
	v_mul_f32_e32 v6, 0x42800000, v7
	v_cvt_pk_fp8_f32 v10, v0, v6 op_sel:[0,0,1]
	v_mul_f32_e32 v0, v8, v76
	global_store_dword v[4:5], v10, off offset:16
	s_waitcnt vmcnt(15)
; __device__ __forceinline__ float bf_lo(unsigned w) { return __uint_as_float(w << 16); }
; __device__ __forceinline__ float bf_hi(unsigned w) { return __uint_as_float(w & 0xffff0000u); }
; __device__ __forceinline__ float siluf_(float v) { return v * sigmoidf_(v); }
; __device__ __forceinline__ void attn_block(const Params& p, LAS unsigned char* lds, int h, int qb) {
;     ...
;         for (int rq = 0; rq < 4; ++rq) { const int dv = d0 * 32 + 8 * rq + 4 * hi; const u32x2 zz = *(const u32x2*)(zp + dv);
;             const float y0 = o[d0][rq * 4 + 0] * il * siluf_(bf_lo(zz.x)), y1 = o[d0][rq * 4 + 1] * il * siluf_(bf_hi(zz.x));
;             const float y2 = o[d0][rq * 4 + 2] * il * siluf_(bf_lo(zz.y)), y3 = o[d0][rq * 4 + 3] * il * siluf_(bf_hi(zz.y));
;             int x8 = __builtin_amdgcn_cvt_pk_fp8_f32(y0 * 64.f, y1 * 64.f, 0, false); x8 = __builtin_amdgcn_cvt_pk_fp8_f32(y2 * 64.f, y3 * 64.f, x8, true);
;             *(int*)(ya8 + (size_t)qrow * 1024 + h * 128 + dv) = x8; }
	v_mov_b32_e32 v6, v134
	v_mov_b32_e32 v7, v135
	v_lshlrev_b32_e32 v9, 16, v6
	v_mul_f32_e32 v10, 0xbfb8aa3b, v9
	v_exp_f32_e32 v10, v10
	v_and_b32_e32 v6, 0xffff0000, v6
	v_add_f32_e32 v10, 1.0, v10
	v_rcp_f32_e32 v10, v10
	s_nop 0
	v_mul_f32_e32 v9, v10, v9
	v_mul_f32_e32 v10, 0xbfb8aa3b, v6
	v_exp_f32_e32 v10, v10
	v_mul_f32_e32 v0, v0, v9
	v_mul_f32_e32 v9, v8, v77
	v_mul_f32_e32 v0, 0x42800000, v0
	v_add_f32_e32 v10, 1.0, v10
	v_rcp_f32_e32 v10, v10
	s_nop 0
	v_mul_f32_e32 v6, v10, v6
	v_lshlrev_b32_e32 v10, 16, v7
	v_mul_f32_e32 v11, 0xbfb8aa3b, v10
	v_exp_f32_e32 v11, v11
	v_and_b32_e32 v7, 0xffff0000, v7
	v_mul_f32_e32 v6, v9, v6
	v_mul_f32_e32 v9, v8, v78
	v_add_f32_e32 v11, 1.0, v11
	v_rcp_f32_e32 v11, v11
	v_mul_f32_e32 v6, 0x42800000, v6
	v_mul_f32_e32 v10, v11, v10
	v_mul_f32_e32 v11, 0xbfb8aa3b, v7
	v_exp_f32_e32 v11, v11
	v_mul_f32_e32 v9, v9, v10
	v_mul_f32_e32 v10, v8, v79
	v_add_f32_e32 v11, 1.0, v11
	v_rcp_f32_e32 v11, v11
	s_nop 0
	v_mul_f32_e32 v7, v11, v7
	v_mul_f32_e32 v7, v10, v7
	v_mov_b32_e32 v10, v1
	v_cvt_pk_fp8_f32 v10, v0, v6
	v_mul_f32_e32 v0, 0x42800000, v9
	v_mul_f32_e32 v6, 0x42800000, v7
	v_cvt_pk_fp8_f32 v10, v0, v6 op_sel:[0,0,1]
	v_mul_f32_e32 v0, v8, v48
	global_store_dword v[4:5], v10, off offset:24
	s_waitcnt vmcnt(15)
	v_mov_b32_e32 v6, v136
	v_mov_b32_e32 v7, v137
	v_lshlrev_b32_e32 v9, 16, v6
	v_mul_f32_e32 v10, 0xbfb8aa3b, v9
	v_exp_f32_e32 v10, v10
	v_and_b32_e32 v6, 0xffff0000, v6
	v_add_f32_e32 v10, 1.0, v10
	v_rcp_f32_e32 v10, v10
	s_nop 0
	v_mul_f32_e32 v9, v10, v9
	v_mul_f32_e32 v10, 0xbfb8aa3b, v6
	v_exp_f32_e32 v10, v10
	v_mul_f32_e32 v0, v0, v9
	v_mul_f32_e32 v9, v8, v49
	v_mul_f32_e32 v0, 0x42800000, v0
	v_add_f32_e32 v10, 1.0, v10
	v_rcp_f32_e32 v10, v10
	s_nop 0
	v_mul_f32_e32 v6, v10, v6
	v_lshlrev_b32_e32 v10, 16, v7
	v_mul_f32_e32 v11, 0xbfb8aa3b, v10
	v_exp_f32_e32 v11, v11
	v_and_b32_e32 v7, 0xffff0000, v7
	v_mul_f32_e32 v6, v9, v6
	v_mul_f32_e32 v9, v8, v50
	v_add_f32_e32 v11, 1.0, v11
	v_rcp_f32_e32 v11, v11
	v_mul_f32_e32 v6, 0x42800000, v6
	v_mul_f32_e32 v10, v11, v10
	v_mul_f32_e32 v11, 0xbfb8aa3b, v7
	v_exp_f32_e32 v11, v11
	v_mul_f32_e32 v9, v9, v10
	v_mul_f32_e32 v10, v8, v51
	v_add_f32_e32 v11, 1.0, v11
	v_rcp_f32_e32 v11, v11
	s_nop 0
	v_mul_f32_e32 v7, v11, v7
	v_mul_f32_e32 v7, v10, v7
	v_mov_b32_e32 v10, v1
	v_cvt_pk_fp8_f32 v10, v0, v6
	v_mul_f32_e32 v0, 0x42800000, v9
	v_mul_f32_e32 v6, 0x42800000, v7
	v_cvt_pk_fp8_f32 v10, v0, v6 op_sel:[0,0,1]
	v_mul_f32_e32 v0, v8, v52
	global_store_dword v[4:5], v10, off offset:32
	s_waitcnt vmcnt(15)
	v_mov_b32_e32 v6, v138
	v_mov_b32_e32 v7, v139
	v_lshlrev_b32_e32 v9, 16, v6
	v_mul_f32_e32 v10, 0xbfb8aa3b, v9
	v_exp_f32_e32 v10, v10
	v_and_b32_e32 v6, 0xffff0000, v6
	v_add_f32_e32 v10, 1.0, v10
	v_rcp_f32_e32 v10, v10
	s_nop 0
	v_mul_f32_e32 v9, v10, v9
	v_mul_f32_e32 v10, 0xbfb8aa3b, v6
	v_exp_f32_e32 v10, v10
	v_mul_f32_e32 v0, v0, v9
	v_mul_f32_e32 v9, v8, v53
	v_mul_f32_e32 v0, 0x42800000, v0
	v_add_f32_e32 v10, 1.0, v10
	v_rcp_f32_e32 v10, v10
	s_nop 0
	v_mul_f32_e32 v6, v10, v6
	v_lshlrev_b32_e32 v10, 16, v7
	v_mul_f32_e32 v11, 0xbfb8aa3b, v10
	v_exp_f32_e32 v11, v11
	v_and_b32_e32 v7, 0xffff0000, v7
	v_mul_f32_e32 v6, v9, v6
	v_mul_f32_e32 v9, v8, v54
	v_add_f32_e32 v11, 1.0, v11
	v_rcp_f32_e32 v11, v11
	v_mul_f32_e32 v6, 0x42800000, v6
	v_mul_f32_e32 v10, v11, v10
	v_mul_f32_e32 v11, 0xbfb8aa3b, v7
	v_exp_f32_e32 v11, v11
	v_mul_f32_e32 v9, v9, v10
	v_mul_f32_e32 v10, v8, v55
	v_add_f32_e32 v11, 1.0, v11
	v_rcp_f32_e32 v11, v11
	s_nop 0
	v_mul_f32_e32 v7, v11, v7
	v_mul_f32_e32 v7, v10, v7
	v_mov_b32_e32 v10, v1
	v_cvt_pk_fp8_f32 v10, v0, v6
	v_mul_f32_e32 v0, 0x42800000, v9
	v_mul_f32_e32 v6, 0x42800000, v7
	v_cvt_pk_fp8_f32 v10, v0, v6 op_sel:[0,0,1]
	v_mul_f32_e32 v0, v8, v56
	global_store_dword v[4:5], v10, off offset:40
	s_waitcnt vmcnt(15)
	v_mov_b32_e32 v6, v140
	v_mov_b32_e32 v7, v141
	v_lshlrev_b32_e32 v9, 16, v6
	v_mul_f32_e32 v10, 0xbfb8aa3b, v9
	v_exp_f32_e32 v10, v10
	v_and_b32_e32 v6, 0xffff0000, v6
	v_add_f32_e32 v10, 1.0, v10
	v_rcp_f32_e32 v10, v10
	s_nop 0
	v_mul_f32_e32 v9, v10, v9
	v_mul_f32_e32 v10, 0xbfb8aa3b, v6
	v_exp_f32_e32 v10, v10
	v_mul_f32_e32 v0, v0, v9
	v_mul_f32_e32 v9, v8, v57
	v_mul_f32_e32 v0, 0x42800000, v0
	v_add_f32_e32 v10, 1.0, v10
	v_rcp_f32_e32 v10, v10
	s_nop 0
	v_mul_f32_e32 v6, v10, v6
	v_lshlrev_b32_e32 v10, 16, v7
	v_mul_f32_e32 v11, 0xbfb8aa3b, v10
	v_exp_f32_e32 v11, v11
	v_and_b32_e32 v7, 0xffff0000, v7
	v_mul_f32_e32 v6, v9, v6
	v_mul_f32_e32 v9, v8, v58
	v_add_f32_e32 v11, 1.0, v11
	v_rcp_f32_e32 v11, v11
	v_mul_f32_e32 v6, 0x42800000, v6
	v_mul_f32_e32 v10, v11, v10
	v_mul_f32_e32 v11, 0xbfb8aa3b, v7
	v_exp_f32_e32 v11, v11
	v_mul_f32_e32 v9, v9, v10
	v_mul_f32_e32 v10, v8, v59
	v_add_f32_e32 v11, 1.0, v11
	v_rcp_f32_e32 v11, v11
	s_nop 0
	v_mul_f32_e32 v7, v11, v7
	v_mul_f32_e32 v7, v10, v7
	v_mov_b32_e32 v10, v1
	v_cvt_pk_fp8_f32 v10, v0, v6
	v_mul_f32_e32 v0, 0x42800000, v9
	v_mul_f32_e32 v6, 0x42800000, v7
	v_cvt_pk_fp8_f32 v10, v0, v6 op_sel:[0,0,1]
	v_mul_f32_e32 v0, v8, v60
	global_store_dword v[4:5], v10, off offset:48
	s_waitcnt vmcnt(15)
; __device__ __forceinline__ float bf_lo(unsigned w) { return __uint_as_float(w << 16); }
; __device__ __forceinline__ float bf_hi(unsigned w) { return __uint_as_float(w & 0xffff0000u); }
; __device__ __forceinline__ float siluf_(float v) { return v * sigmoidf_(v); }
; __device__ __forceinline__ void attn_block(const Params& p, LAS unsigned char* lds, int h, int qb) {
;     ...
;         for (int rq = 0; rq < 4; ++rq) { const int dv = d0 * 32 + 8 * rq + 4 * hi; const u32x2 zz = *(const u32x2*)(zp + dv);
;             const float y0 = o[d0][rq * 4 + 0] * il * siluf_(bf_lo(zz.x)), y1 = o[d0][rq * 4 + 1] * il * siluf_(bf_hi(zz.x));
;             const float y2 = o[d0][rq * 4 + 2] * il * siluf_(bf_lo(zz.y)), y3 = o[d0][rq * 4 + 3] * il * siluf_(bf_hi(zz.y));
;             int x8 = __builtin_amdgcn_cvt_pk_fp8_f32(y0 * 64.f, y1 * 64.f, 0, false); x8 = __builtin_amdgcn_cvt_pk_fp8_f32(y2 * 64.f, y3 * 64.f, x8, true);
;             *(int*)(ya8 + (size_t)qrow * 1024 + h * 128 + dv) = x8; }
	v_mov_b32_e32 v6, v142
	v_mov_b32_e32 v7, v143
	v_lshlrev_b32_e32 v9, 16, v6
	v_mul_f32_e32 v10, 0xbfb8aa3b, v9
	v_exp_f32_e32 v10, v10
	v_and_b32_e32 v6, 0xffff0000, v6
	v_add_f32_e32 v10, 1.0, v10
	v_rcp_f32_e32 v10, v10
	s_nop 0
	v_mul_f32_e32 v9, v10, v9
	v_mul_f32_e32 v10, 0xbfb8aa3b, v6
	v_exp_f32_e32 v10, v10
	v_mul_f32_e32 v0, v0, v9
	v_mul_f32_e32 v9, v8, v61
	v_mul_f32_e32 v0, 0x42800000, v0
	v_add_f32_e32 v10, 1.0, v10
	v_rcp_f32_e32 v10, v10
	s_nop 0
	v_mul_f32_e32 v6, v10, v6
	v_lshlrev_b32_e32 v10, 16, v7
	v_mul_f32_e32 v11, 0xbfb8aa3b, v10
	v_exp_f32_e32 v11, v11
	v_and_b32_e32 v7, 0xffff0000, v7
	v_mul_f32_e32 v6, v9, v6
	v_mul_f32_e32 v9, v8, v62
	v_add_f32_e32 v11, 1.0, v11
	v_rcp_f32_e32 v11, v11
	v_mul_f32_e32 v6, 0x42800000, v6
	v_mul_f32_e32 v10, v11, v10
	v_mul_f32_e32 v11, 0xbfb8aa3b, v7
	v_exp_f32_e32 v11, v11
	v_mul_f32_e32 v9, v9, v10
	v_mul_f32_e32 v10, v8, v63
	v_add_f32_e32 v11, 1.0, v11
	v_rcp_f32_e32 v11, v11
	s_nop 0
	v_mul_f32_e32 v7, v11, v7
	v_mul_f32_e32 v7, v10, v7
	v_mov_b32_e32 v10, v1
	v_cvt_pk_fp8_f32 v10, v0, v6
	v_mul_f32_e32 v0, 0x42800000, v9
	v_mul_f32_e32 v6, 0x42800000, v7
	v_cvt_pk_fp8_f32 v10, v0, v6 op_sel:[0,0,1]
	v_mul_f32_e32 v0, v8, v32
	global_store_dword v[4:5], v10, off offset:56
	s_waitcnt vmcnt(15)
	v_mov_b32_e32 v6, v144
	v_mov_b32_e32 v7, v145
	v_lshlrev_b32_e32 v9, 16, v6
	v_mul_f32_e32 v10, 0xbfb8aa3b, v9
	v_exp_f32_e32 v10, v10
	v_and_b32_e32 v6, 0xffff0000, v6
	v_add_f32_e32 v10, 1.0, v10
	v_rcp_f32_e32 v10, v10
	s_nop 0
	v_mul_f32_e32 v9, v10, v9
	v_mul_f32_e32 v10, 0xbfb8aa3b, v6
	v_exp_f32_e32 v10, v10
	v_mul_f32_e32 v0, v0, v9
	v_mul_f32_e32 v9, v8, v33
	v_mul_f32_e32 v0, 0x42800000, v0
	v_add_f32_e32 v10, 1.0, v10
	v_rcp_f32_e32 v10, v10
	s_nop 0
	v_mul_f32_e32 v6, v10, v6
	v_lshlrev_b32_e32 v10, 16, v7
	v_mul_f32_e32 v11, 0xbfb8aa3b, v10
	v_exp_f32_e32 v11, v11
	v_and_b32_e32 v7, 0xffff0000, v7
	v_mul_f32_e32 v6, v9, v6
	v_mul_f32_e32 v9, v8, v34
	v_add_f32_e32 v11, 1.0, v11
	v_rcp_f32_e32 v11, v11
	v_mul_f32_e32 v6, 0x42800000, v6
	v_mul_f32_e32 v10, v11, v10
	v_mul_f32_e32 v11, 0xbfb8aa3b, v7
	v_exp_f32_e32 v11, v11
	v_mul_f32_e32 v9, v9, v10
	v_mul_f32_e32 v10, v8, v35
	v_add_f32_e32 v11, 1.0, v11
	v_rcp_f32_e32 v11, v11
	s_nop 0
	v_mul_f32_e32 v7, v11, v7
	v_mul_f32_e32 v7, v10, v7
	v_mov_b32_e32 v10, v1
	v_cvt_pk_fp8_f32 v10, v0, v6
	v_mul_f32_e32 v0, 0x42800000, v9
	v_mul_f32_e32 v6, 0x42800000, v7
	v_cvt_pk_fp8_f32 v10, v0, v6 op_sel:[0,0,1]
	v_mul_f32_e32 v0, v8, v36
	global_store_dword v[4:5], v10, off offset:64
	s_waitcnt vmcnt(15)
	v_mov_b32_e32 v6, v146
	v_mov_b32_e32 v7, v147
	v_lshlrev_b32_e32 v9, 16, v6
	v_mul_f32_e32 v10, 0xbfb8aa3b, v9
	v_exp_f32_e32 v10, v10
	v_and_b32_e32 v6, 0xffff0000, v6
	v_add_f32_e32 v10, 1.0, v10
	v_rcp_f32_e32 v10, v10
	s_nop 0
	v_mul_f32_e32 v9, v10, v9
	v_mul_f32_e32 v10, 0xbfb8aa3b, v6
	v_exp_f32_e32 v10, v10
	v_mul_f32_e32 v0, v0, v9
	v_mul_f32_e32 v9, v8, v37
	v_mul_f32_e32 v0, 0x42800000, v0
	v_add_f32_e32 v10, 1.0, v10
	v_rcp_f32_e32 v10, v10
	s_nop 0
	v_mul_f32_e32 v6, v10, v6
	v_lshlrev_b32_e32 v10, 16, v7
	v_mul_f32_e32 v11, 0xbfb8aa3b, v10
	v_exp_f32_e32 v11, v11
	v_and_b32_e32 v7, 0xffff0000, v7
	v_mul_f32_e32 v6, v9, v6
	v_mul_f32_e32 v9, v8, v38
	v_add_f32_e32 v11, 1.0, v11
	v_rcp_f32_e32 v11, v11
	v_mul_f32_e32 v6, 0x42800000, v6
	v_mul_f32_e32 v10, v11, v10
	v_mul_f32_e32 v11, 0xbfb8aa3b, v7
	v_exp_f32_e32 v11, v11
	v_mul_f32_e32 v9, v9, v10
	v_mul_f32_e32 v10, v8, v39
	v_add_f32_e32 v11, 1.0, v11
	v_rcp_f32_e32 v11, v11
	s_nop 0
	v_mul_f32_e32 v7, v11, v7
	v_mul_f32_e32 v7, v10, v7
	v_mov_b32_e32 v10, v1
	v_cvt_pk_fp8_f32 v10, v0, v6
	v_mul_f32_e32 v0, 0x42800000, v9
	v_mul_f32_e32 v6, 0x42800000, v7
	v_cvt_pk_fp8_f32 v10, v0, v6 op_sel:[0,0,1]
	v_mul_f32_e32 v0, v8, v40
	global_store_dword v[4:5], v10, off offset:72
	s_waitcnt vmcnt(15)
	v_mov_b32_e32 v6, v148
	v_mov_b32_e32 v7, v149
	v_lshlrev_b32_e32 v9, 16, v6
	v_mul_f32_e32 v10, 0xbfb8aa3b, v9
	v_exp_f32_e32 v10, v10
	v_and_b32_e32 v6, 0xffff0000, v6
	v_add_f32_e32 v10, 1.0, v10
	v_rcp_f32_e32 v10, v10
	s_nop 0
	v_mul_f32_e32 v9, v10, v9
	v_mul_f32_e32 v10, 0xbfb8aa3b, v6
	v_exp_f32_e32 v10, v10
	v_mul_f32_e32 v0, v0, v9
	v_mul_f32_e32 v9, v8, v41
	v_mul_f32_e32 v0, 0x42800000, v0
	v_add_f32_e32 v10, 1.0, v10
	v_rcp_f32_e32 v10, v10
	s_nop 0
	v_mul_f32_e32 v6, v10, v6
	v_lshlrev_b32_e32 v10, 16, v7
	v_mul_f32_e32 v11, 0xbfb8aa3b, v10
	v_exp_f32_e32 v11, v11
	v_and_b32_e32 v7, 0xffff0000, v7
	v_mul_f32_e32 v6, v9, v6
	v_mul_f32_e32 v9, v8, v42
	v_add_f32_e32 v11, 1.0, v11
	v_rcp_f32_e32 v11, v11
	v_mul_f32_e32 v6, 0x42800000, v6
	v_mul_f32_e32 v10, v11, v10
	v_mul_f32_e32 v11, 0xbfb8aa3b, v7
	v_exp_f32_e32 v11, v11
	v_mul_f32_e32 v9, v9, v10
	v_mul_f32_e32 v10, v8, v43
	v_add_f32_e32 v11, 1.0, v11
	v_rcp_f32_e32 v11, v11
	s_nop 0
	v_mul_f32_e32 v7, v11, v7
	v_mul_f32_e32 v7, v10, v7
	v_mov_b32_e32 v10, v1
	v_cvt_pk_fp8_f32 v10, v0, v6
	v_mul_f32_e32 v0, 0x42800000, v9
	v_mul_f32_e32 v6, 0x42800000, v7
	v_cvt_pk_fp8_f32 v10, v0, v6 op_sel:[0,0,1]
	v_mul_f32_e32 v0, v8, v44
	global_store_dword v[4:5], v10, off offset:80
	s_waitcnt vmcnt(15)
; __device__ __forceinline__ float bf_lo(unsigned w) { return __uint_as_float(w << 16); }
; __device__ __forceinline__ float bf_hi(unsigned w) { return __uint_as_float(w & 0xffff0000u); }
; __device__ __forceinline__ float siluf_(float v) { return v * sigmoidf_(v); }
; __device__ __forceinline__ int obid() { int t = blockIdx.x; asm volatile("" : "+s"(t)); return t; }
; __device__ __forceinline__ int ogdim() { int t = gridDim.x; asm volatile("" : "+s"(t)); return t; }
; __device__ __forceinline__ void attn_block(const Params& p, LAS unsigned char* lds, int h, int qb) {
;     ...
;         for (int rq = 0; rq < 4; ++rq) { const int dv = d0 * 32 + 8 * rq + 4 * hi; const u32x2 zz = *(const u32x2*)(zp + dv);
;             const float y0 = o[d0][rq * 4 + 0] * il * siluf_(bf_lo(zz.x)), y1 = o[d0][rq * 4 + 1] * il * siluf_(bf_hi(zz.x));
;             const float y2 = o[d0][rq * 4 + 2] * il * siluf_(bf_lo(zz.y)), y3 = o[d0][rq * 4 + 3] * il * siluf_(bf_hi(zz.y));
;             int x8 = __builtin_amdgcn_cvt_pk_fp8_f32(y0 * 64.f, y1 * 64.f, 0, false); x8 = __builtin_amdgcn_cvt_pk_fp8_f32(y2 * 64.f, y3 * 64.f, x8, true);
;             *(int*)(ya8 + (size_t)qrow * 1024 + h * 128 + dv) = x8; }
; __device__ __forceinline__ void attn_phase(const Params& p, LAS unsigned char* lds) {
;     for (int it = obid(); it < 256; it += ogdim()) {
;         const int h = it & 7, x = it >> 3;
;         for (int pass = 0; pass < 2; ++pass) attn_block(p, lds, h, pass ? x : 63 - x);
	v_mov_b32_e32 v6, v150
	v_mov_b32_e32 v7, v151
	v_lshlrev_b32_e32 v9, 16, v6
	v_mul_f32_e32 v10, 0xbfb8aa3b, v9
	v_exp_f32_e32 v10, v10
	v_and_b32_e32 v6, 0xffff0000, v6
	v_add_f32_e32 v10, 1.0, v10
	v_rcp_f32_e32 v10, v10
	s_nop 0
	v_mul_f32_e32 v9, v10, v9
	v_mul_f32_e32 v10, 0xbfb8aa3b, v6
	v_exp_f32_e32 v10, v10
	v_mul_f32_e32 v0, v0, v9
	v_mul_f32_e32 v9, v8, v45
	v_mul_f32_e32 v0, 0x42800000, v0
	v_add_f32_e32 v10, 1.0, v10
	v_rcp_f32_e32 v10, v10
	s_nop 0
	v_mul_f32_e32 v6, v10, v6
	v_lshlrev_b32_e32 v10, 16, v7
	v_mul_f32_e32 v11, 0xbfb8aa3b, v10
	v_exp_f32_e32 v11, v11
	v_and_b32_e32 v7, 0xffff0000, v7
	v_mul_f32_e32 v6, v9, v6
	v_mul_f32_e32 v9, v8, v46
	v_add_f32_e32 v11, 1.0, v11
	v_rcp_f32_e32 v11, v11
	v_mul_f32_e32 v6, 0x42800000, v6
	v_mul_f32_e32 v10, v11, v10
	v_mul_f32_e32 v11, 0xbfb8aa3b, v7
	v_exp_f32_e32 v11, v11
	v_mul_f32_e32 v9, v9, v10
	v_mul_f32_e32 v10, v8, v47
	v_add_f32_e32 v11, 1.0, v11
	v_rcp_f32_e32 v11, v11
	s_nop 0
	v_mul_f32_e32 v7, v11, v7
	v_mul_f32_e32 v7, v10, v7
	v_mov_b32_e32 v10, v1
	v_cvt_pk_fp8_f32 v10, v0, v6
	v_mul_f32_e32 v0, 0x42800000, v9
	v_mul_f32_e32 v6, 0x42800000, v7
	v_cvt_pk_fp8_f32 v10, v0, v6 op_sel:[0,0,1]
	v_mul_f32_e32 v0, v8, v16
	global_store_dword v[4:5], v10, off offset:88
	s_waitcnt vmcnt(15)
	v_mov_b32_e32 v6, v152
	v_mov_b32_e32 v7, v153
	v_lshlrev_b32_e32 v9, 16, v6
	v_mul_f32_e32 v10, 0xbfb8aa3b, v9
	v_exp_f32_e32 v10, v10
	v_and_b32_e32 v6, 0xffff0000, v6
	v_add_f32_e32 v10, 1.0, v10
	v_rcp_f32_e32 v10, v10
	s_nop 0
	v_mul_f32_e32 v9, v10, v9
	v_mul_f32_e32 v10, 0xbfb8aa3b, v6
	v_exp_f32_e32 v10, v10
	v_mul_f32_e32 v0, v0, v9
	v_mul_f32_e32 v9, v8, v17
	v_mul_f32_e32 v0, 0x42800000, v0
	v_add_f32_e32 v10, 1.0, v10
	v_rcp_f32_e32 v10, v10
	s_nop 0
	v_mul_f32_e32 v6, v10, v6
	v_lshlrev_b32_e32 v10, 16, v7
	v_mul_f32_e32 v11, 0xbfb8aa3b, v10
	v_exp_f32_e32 v11, v11
	v_and_b32_e32 v7, 0xffff0000, v7
	v_mul_f32_e32 v6, v9, v6
	v_mul_f32_e32 v9, v8, v18
	v_add_f32_e32 v11, 1.0, v11
	v_rcp_f32_e32 v11, v11
	v_mul_f32_e32 v6, 0x42800000, v6
	v_mul_f32_e32 v10, v11, v10
	v_mul_f32_e32 v11, 0xbfb8aa3b, v7
	v_exp_f32_e32 v11, v11
	v_mul_f32_e32 v9, v9, v10
	v_mul_f32_e32 v10, v8, v19
	v_add_f32_e32 v11, 1.0, v11
	v_rcp_f32_e32 v11, v11
	s_nop 0
	v_mul_f32_e32 v7, v11, v7
	v_mul_f32_e32 v7, v10, v7
	v_mov_b32_e32 v10, v1
	v_cvt_pk_fp8_f32 v10, v0, v6
	v_mul_f32_e32 v0, 0x42800000, v9
	v_mul_f32_e32 v6, 0x42800000, v7
	v_cvt_pk_fp8_f32 v10, v0, v6 op_sel:[0,0,1]
	v_mul_f32_e32 v0, v8, v20
	global_store_dword v[4:5], v10, off offset:96
	s_waitcnt vmcnt(15)
	v_mov_b32_e32 v6, v154
	v_mov_b32_e32 v7, v155
	v_lshlrev_b32_e32 v9, 16, v6
	v_mul_f32_e32 v10, 0xbfb8aa3b, v9
	v_exp_f32_e32 v10, v10
	v_and_b32_e32 v6, 0xffff0000, v6
	v_add_f32_e32 v10, 1.0, v10
	v_rcp_f32_e32 v10, v10
	s_nop 0
	v_mul_f32_e32 v9, v10, v9
	v_mul_f32_e32 v10, 0xbfb8aa3b, v6
	v_exp_f32_e32 v10, v10
	v_mul_f32_e32 v0, v0, v9
	v_mul_f32_e32 v9, v8, v21
	v_mul_f32_e32 v0, 0x42800000, v0
	v_add_f32_e32 v10, 1.0, v10
	v_rcp_f32_e32 v10, v10
	s_nop 0
	v_mul_f32_e32 v6, v10, v6
	v_lshlrev_b32_e32 v10, 16, v7
	v_mul_f32_e32 v11, 0xbfb8aa3b, v10
	v_exp_f32_e32 v11, v11
	v_and_b32_e32 v7, 0xffff0000, v7
	v_mul_f32_e32 v6, v9, v6
	v_mul_f32_e32 v9, v8, v22
	v_add_f32_e32 v11, 1.0, v11
	v_rcp_f32_e32 v11, v11
	v_mul_f32_e32 v6, 0x42800000, v6
	v_mul_f32_e32 v10, v11, v10
	v_mul_f32_e32 v11, 0xbfb8aa3b, v7
	v_exp_f32_e32 v11, v11
	v_mul_f32_e32 v9, v9, v10
	v_mul_f32_e32 v10, v8, v23
	v_add_f32_e32 v11, 1.0, v11
	v_rcp_f32_e32 v11, v11
	s_nop 0
	v_mul_f32_e32 v7, v11, v7
	v_mul_f32_e32 v7, v10, v7
	v_mov_b32_e32 v10, v1
	v_cvt_pk_fp8_f32 v10, v0, v6
	v_mul_f32_e32 v0, 0x42800000, v9
	v_mul_f32_e32 v6, 0x42800000, v7
	v_cvt_pk_fp8_f32 v10, v0, v6 op_sel:[0,0,1]
	v_mul_f32_e32 v0, v8, v24
	global_store_dword v[4:5], v10, off offset:104
	s_waitcnt vmcnt(15)
	v_mov_b32_e32 v6, v156
	v_mov_b32_e32 v7, v157
	v_lshlrev_b32_e32 v9, 16, v6
	v_mul_f32_e32 v10, 0xbfb8aa3b, v9
	v_exp_f32_e32 v10, v10
	v_and_b32_e32 v6, 0xffff0000, v6
	v_add_f32_e32 v10, 1.0, v10
	v_rcp_f32_e32 v10, v10
	s_nop 0
	v_mul_f32_e32 v9, v10, v9
	v_mul_f32_e32 v10, 0xbfb8aa3b, v6
	v_exp_f32_e32 v10, v10
	v_mul_f32_e32 v0, v0, v9
	v_mul_f32_e32 v9, v8, v25
	v_mul_f32_e32 v0, 0x42800000, v0
	v_add_f32_e32 v10, 1.0, v10
	v_rcp_f32_e32 v10, v10
	s_nop 0
	v_mul_f32_e32 v6, v10, v6
	v_lshlrev_b32_e32 v10, 16, v7
	v_mul_f32_e32 v11, 0xbfb8aa3b, v10
	v_exp_f32_e32 v11, v11
	v_and_b32_e32 v7, 0xffff0000, v7
	v_mul_f32_e32 v6, v9, v6
	v_mul_f32_e32 v9, v8, v26
	v_add_f32_e32 v11, 1.0, v11
	v_rcp_f32_e32 v11, v11
	v_mul_f32_e32 v6, 0x42800000, v6
	v_mul_f32_e32 v10, v11, v10
	v_mul_f32_e32 v11, 0xbfb8aa3b, v7
	v_exp_f32_e32 v11, v11
	v_mul_f32_e32 v9, v9, v10
	v_mul_f32_e32 v10, v8, v27
	v_add_f32_e32 v11, 1.0, v11
	v_rcp_f32_e32 v11, v11
	s_nop 0
	v_mul_f32_e32 v7, v11, v7
	v_mul_f32_e32 v7, v10, v7
	v_mov_b32_e32 v10, v1
	v_cvt_pk_fp8_f32 v10, v0, v6
	v_mul_f32_e32 v0, 0x42800000, v9
	v_mul_f32_e32 v6, 0x42800000, v7
	v_cvt_pk_fp8_f32 v10, v0, v6 op_sel:[0,0,1]
	v_mul_f32_e32 v0, v8, v28
	global_store_dword v[4:5], v10, off offset:112
	s_waitcnt vmcnt(15)
	v_mov_b32_e32 v2, v158
	v_mov_b32_e32 v3, v159
	v_lshlrev_b32_e32 v6, 16, v2
	v_mul_f32_e32 v7, 0xbfb8aa3b, v6
	v_exp_f32_e32 v7, v7
	v_and_b32_e32 v2, 0xffff0000, v2
	v_add_f32_e32 v7, 1.0, v7
	v_rcp_f32_e32 v7, v7
	s_nop 0
	v_mul_f32_e32 v6, v7, v6
	v_mul_f32_e32 v7, 0xbfb8aa3b, v2
	v_exp_f32_e32 v7, v7
	v_mul_f32_e32 v0, v0, v6
	v_mul_f32_e32 v6, v8, v29
	v_mul_f32_e32 v0, 0x42800000, v0
	v_add_f32_e32 v7, 1.0, v7
	v_rcp_f32_e32 v7, v7
	s_nop 0
	v_mul_f32_e32 v2, v7, v2
	v_lshlrev_b32_e32 v7, 16, v3
	v_mul_f32_e32 v9, 0xbfb8aa3b, v7
	v_exp_f32_e32 v9, v9
	v_mul_f32_e32 v2, v6, v2
	v_mul_f32_e32 v6, v8, v30
	v_and_b32_e32 v3, 0xffff0000, v3
	v_add_f32_e32 v9, 1.0, v9
	v_rcp_f32_e32 v9, v9
	v_mul_f32_e32 v2, 0x42800000, v2
	v_mul_f32_e32 v7, v9, v7
	v_mul_f32_e32 v6, v6, v7
	v_mul_f32_e32 v7, v8, v31
	v_mul_f32_e32 v8, 0xbfb8aa3b, v3
	v_exp_f32_e32 v8, v8
	s_nop 0
	v_add_f32_e32 v8, 1.0, v8
	v_rcp_f32_e32 v8, v8
	s_nop 0
	v_mul_f32_e32 v3, v8, v3
	v_mul_f32_e32 v3, v7, v3
	v_mov_b32_e32 v7, v1
	v_cvt_pk_fp8_f32 v7, v0, v2
	v_mul_f32_e32 v0, 0x42800000, v6
	v_mul_f32_e32 v2, 0x42800000, v3
	v_cvt_pk_fp8_f32 v7, v0, v2 op_sel:[0,0,1]
	global_store_dword v[4:5], v7, off offset:120
	s_cbranch_vccnz .LBB0_320

; template <int k> __device__ __forceinline__ void fin_snip(f32x16& p0, f32x16& p1, float alpha, float& l_reg, float& ps, bf16x8& pa0, bf16x8& pa1, bf16x8& pa2, bf16x8& pa3) {
;     if constexpr (k < 8) { p1[2 * k] = __builtin_amdgcn_exp2f(p1[2 * k]); p1[2 * k + 1] = __builtin_amdgcn_exp2f(p1[2 * k + 1]); }
;     else if constexpr (k < 16) { constexpr int j = 2 * (k - 8); const float a = (p0[j] + p0[j + 1]) + (p1[j] + p1[j + 1]); ps = (k == 8) ? a : ps + a; }
;     else if constexpr (k == 16) { auto rr = __builtin_amdgcn_permlane32_swap(__float_as_uint(ps), __float_as_uint(ps), false, false);
;         ps = __uint_as_float(rr[0]) + __uint_as_float(rr[1]); l_reg = l_reg * alpha + ps; }
;     else if constexpr (k == 17) { PK4(p0, 0, pa0); }
;     else if constexpr (k == 18) { PK4(p0, 8, pa1); }
;     else if constexpr (k == 19) { PK4(p1, 0, pa2); }
;     else if constexpr (k == 20) { PK4(p1, 8, pa3); }
; }
; template <int k> __device__ __forceinline__ void par_snip(f32x16& p0, f32x16& p1, float& m_reg, float& pmax, float& alpha, float& mnL, float msk) {
;     constexpr float C2 = 1.4426950408889634f * SCALE;
;     if constexpr (k < 4) { constexpr int j = 4 * k; const float a = fmaxf(fmaxf(p0[j], p0[j + 1]), fmaxf(p0[j + 2], p0[j + 3])), b = fmaxf(fmaxf(p1[j], p1[j + 1]), fmaxf(p1[j + 2], p1[j + 3]));
;         pmax = (k == 0) ? fmaxf(a, b) : fmaxf(pmax, fmaxf(a, b)); }
;     else if constexpr (k == 4) { pmax += msk;
;         { auto rr = __builtin_amdgcn_permlane32_swap(__float_as_uint(pmax), __float_as_uint(pmax), false, false); pmax = fmaxf(__uint_as_float(rr[0]), __uint_as_float(rr[1])); }
;         const bool defer = __all((pmax - m_reg) * SCALE <= THR);
;         const float mn = defer ? m_reg : fmaxf(m_reg, pmax);
;         alpha = __builtin_amdgcn_exp2f((m_reg - mn) * C2); m_reg = mn; mnL = fmaf(-mn, C2, msk); }
;     else if constexpr (k < 9) { constexpr int j = 4 * (k - 5);
; #pragma unroll
;         for (int e = 0; e < 4; ++e) { p0[j + e] = fmaf(p0[j + e], C2, mnL); p1[j + e] = fmaf(p1[j + e], C2, mnL); } }
;     else if constexpr (k < 15) { constexpr int j = 2 * (k - 9); p0[j] = __builtin_amdgcn_exp2f(p0[j]); p0[j + 1] = __builtin_amdgcn_exp2f(p0[j + 1]); }
;     else if constexpr (k == 15) {
; #pragma unroll
;         for (int e = 12; e < 16; ++e) p0[e] = __builtin_amdgcn_exp2f(p0[e]); }
; }
.LBB0_328:
	s_setprio 1
	s_cmp_gt_i32 s86, s84
	s_cselect_b64 vcc, -1, 0
	v_cndmask_b32_e32 v216, 0, v223, vcc
	ds_read_b128 v[2:5], v226 offset:0
	ds_read_b128 v[6:9], v226 offset:0x3000
	ds_read_b128 v[10:13], v227 offset:0
	ds_read_b128 v[176:179], v227 offset:0x3000
	s_nop 0
	s_waitcnt lgkmcnt(2)
	s_nop 0
	v_mfma_f32_32x32x16_bf16 v[96:111], v[2:5], v[128:131], 0
	v_exp_f32_e32 v214, v214
	v_exp_f32_e32 v215, v215
	v_mfma_f32_32x32x16_bf16 v[112:127], v[6:9], v[128:131], 0
	v_exp_f32_e32 v212, v212
	v_exp_f32_e32 v213, v213
	ds_read_b128 v[2:5], v228 offset:0
	ds_read_b128 v[6:9], v228 offset:0x3000
	s_waitcnt lgkmcnt(2)
	s_nop 0
	v_mfma_f32_32x32x16_bf16 v[96:111], v[10:13], v[132:135], v[96:111]
	v_exp_f32_e32 v210, v210
	v_exp_f32_e32 v211, v211
	v_mfma_f32_32x32x16_bf16 v[112:127], v[176:179], v[132:135], v[112:127]
	v_exp_f32_e32 v208, v208
	v_exp_f32_e32 v209, v209
	ds_read_b128 v[10:13], v229 offset:0
	ds_read_b128 v[176:179], v229 offset:0x3000
	s_waitcnt lgkmcnt(2)
	s_nop 0
	v_mfma_f32_32x32x16_bf16 v[96:111], v[2:5], v[136:139], v[96:111]
	v_exp_f32_e32 v206, v206
	v_exp_f32_e32 v207, v207
	v_mfma_f32_32x32x16_bf16 v[112:127], v[6:9], v[136:139], v[112:127]
	v_exp_f32_e32 v204, v204
	v_exp_f32_e32 v205, v205
	ds_read_b128 v[2:5], v226 offset:0x80
	ds_read_b128 v[6:9], v226 offset:0x3080
	s_waitcnt lgkmcnt(2)
	s_nop 0
	v_mfma_f32_32x32x16_bf16 v[96:111], v[10:13], v[140:143], v[96:111]
	v_exp_f32_e32 v202, v202
	v_exp_f32_e32 v203, v203
	v_mfma_f32_32x32x16_bf16 v[112:127], v[176:179], v[140:143], v[112:127]
	v_exp_f32_e32 v200, v200
	v_exp_f32_e32 v201, v201
	ds_read_b128 v[10:13], v227 offset:0x80
	ds_read_b128 v[176:179], v227 offset:0x3080
	s_waitcnt lgkmcnt(2)
	s_nop 0
	v_mfma_f32_32x32x16_bf16 v[96:111], v[2:5], v[144:147], v[96:111]
	v_add_f32_e32 v0, v80, v81
	v_add_f32_e32 v2, v214, v215
	v_add_f32_e32 v0, v0, v2
	v_mfma_f32_32x32x16_bf16 v[112:127], v[6:9], v[144:147], v[112:127]
	v_add_f32_e32 v2, v82, v83
	v_add_f32_e32 v3, v212, v213
	v_add_f32_e32 v2, v2, v3
	v_add_f32_e32 v0, v0, v2
	ds_read_b128 v[2:5], v228 offset:0x80
	ds_read_b128 v[6:9], v228 offset:0x3080
	s_waitcnt lgkmcnt(2)
	s_nop 0
	v_mfma_f32_32x32x16_bf16 v[96:111], v[10:13], v[148:151], v[96:111]
	v_add_f32_e32 v10, v84, v85
	v_add_f32_e32 v11, v210, v211
	v_add_f32_e32 v10, v10, v11
	v_add_f32_e32 v0, v10, v0
	v_mfma_f32_32x32x16_bf16 v[112:127], v[176:179], v[148:151], v[112:127]
	v_add_f32_e32 v10, v86, v87
	v_add_f32_e32 v11, v208, v209
	v_add_f32_e32 v10, v10, v11
	v_add_f32_e32 v0, v10, v0
	ds_read_b128 v[10:13], v229 offset:0x80
	ds_read_b128 v[176:179], v229 offset:0x3080
	s_waitcnt lgkmcnt(2)
	s_nop 0
	v_mfma_f32_32x32x16_bf16 v[96:111], v[2:5], v[152:155], v[96:111]
	v_add_f32_e32 v2, v88, v89
	v_add_f32_e32 v3, v206, v207
	v_add_f32_e32 v2, v2, v3
	v_add_f32_e32 v0, v2, v0
	v_mfma_f32_32x32x16_bf16 v[112:127], v[6:9], v[152:155], v[112:127]
	v_add_f32_e32 v2, v90, v91
	v_add_f32_e32 v3, v204, v205
	v_add_f32_e32 v2, v2, v3
	v_add_f32_e32 v0, v2, v0
	ds_read_b128 v[2:5], v226 offset:0x100
	ds_read_b128 v[6:9], v226 offset:0x3100
	s_waitcnt lgkmcnt(2)
	s_nop 0
	v_mfma_f32_32x32x16_bf16 v[96:111], v[10:13], v[156:159], v[96:111]
	v_add_f32_e32 v10, v92, v93
	v_add_f32_e32 v11, v202, v203
	v_add_f32_e32 v10, v10, v11
	v_add_f32_e32 v0, v10, v0
	v_mfma_f32_32x32x16_bf16 v[112:127], v[176:179], v[156:159], v[112:127]
	v_add_f32_e32 v10, v94, v95
	v_add_f32_e32 v11, v200, v201
	v_add_f32_e32 v10, v10, v11
	v_add_f32_e32 v14, v10, v0
	ds_read_b128 v[10:13], v227 offset:0x100
	ds_read_b128 v[176:179], v227 offset:0x3100
	s_waitcnt lgkmcnt(2)
	s_nop 0
	v_mfma_f32_32x32x16_bf16 v[96:111], v[2:5], v[160:163], v[96:111]
	v_mov_b32_e32 v15, v14
	s_nop 1
	v_permlane32_swap_b32_e32 v14, v15
	v_mfma_f32_32x32x16_bf16 v[112:127], v[6:9], v[160:163], v[112:127]
	v_cvt_pk_bf16_f32 v2, v80, v81
	v_cvt_pk_bf16_f32 v3, v82, v83
	v_cvt_pk_bf16_f32 v4, v84, v85
	v_cvt_pk_bf16_f32 v5, v86, v87
	ds_read_b128 v[194:197], v228 offset:0x100
	ds_read_b128 v[232:235], v228 offset:0x3100
	s_waitcnt lgkmcnt(2)
	s_nop 0
	v_mfma_f32_32x32x16_bf16 v[96:111], v[10:13], v[164:167], v[96:111]
	v_cvt_pk_bf16_f32 v6, v88, v89
	v_cvt_pk_bf16_f32 v7, v90, v91
	v_cvt_pk_bf16_f32 v8, v92, v93
	v_cvt_pk_bf16_f32 v9, v94, v95
	v_mfma_f32_32x32x16_bf16 v[112:127], v[176:179], v[164:167], v[112:127]
	v_cvt_pk_bf16_f32 v10, v214, v215
	v_cvt_pk_bf16_f32 v11, v212, v213
	v_cvt_pk_bf16_f32 v12, v210, v211
	v_cvt_pk_bf16_f32 v13, v208, v209
	ds_read_b128 v[236:239], v229 offset:0x100
	ds_read_b128 v[240:243], v229 offset:0x3100
	s_waitcnt lgkmcnt(2)
	s_nop 0
	v_mfma_f32_32x32x16_bf16 v[96:111], v[194:197], v[168:171], v[96:111]
	v_cvt_pk_bf16_f32 v176, v206, v207
	v_cvt_pk_bf16_f32 v177, v204, v205
	v_cvt_pk_bf16_f32 v178, v202, v203
	v_cvt_pk_bf16_f32 v179, v200, v201
	v_mfma_f32_32x32x16_bf16 v[112:127], v[232:235], v[168:171], v[112:127]
	v_add_f32_e32 v247, v14, v15
	v_fma_f32 v245, v192, v245, v247
	s_waitcnt lgkmcnt(0)
	s_nop 0
	v_mfma_f32_32x32x16_bf16 v[96:111], v[236:239], v[172:175], v[96:111]
	v_mfma_f32_32x32x16_bf16 v[112:127], v[240:243], v[172:175], v[112:127]
	s_cmp_eq_u32 s100, 0
	s_cbranch_scc1 .Lmy_mid_a
	s_waitcnt vmcnt(0)
	s_barrier
; #define SBAR() __builtin_amdgcn_sched_barrier(0)
; #define PV_RD(F_, d0) do { constexpr int b_ = V_OFF + v_rd_off(d0, 0, 0); \
;         TRRD(F_[0], b_); TRRD(F_[1], b_ + 2048); TRRD(F_[2], b_ + 4096); TRRD(F_[3], b_ + 6144); TRRD(F_[4], b_ + 8192); TRRD(F_[5], b_ + 10240); TRRD(F_[6], b_ + 12288); TRRD(F_[7], b_ + 14336); } while (0)
; template <int k> __device__ __forceinline__ void par_snip(f32x16& p0, f32x16& p1, float& m_reg, float& pmax, float& alpha, float& mnL, float msk) {
;     constexpr float C2 = 1.4426950408889634f * SCALE;
;     if constexpr (k < 4) { constexpr int j = 4 * k; const float a = fmaxf(fmaxf(p0[j], p0[j + 1]), fmaxf(p0[j + 2], p0[j + 3])), b = fmaxf(fmaxf(p1[j], p1[j + 1]), fmaxf(p1[j + 2], p1[j + 3]));
;         pmax = (k == 0) ? fmaxf(a, b) : fmaxf(pmax, fmaxf(a, b)); }
;     else if constexpr (k == 4) { pmax += msk;
;         { auto rr = __builtin_amdgcn_permlane32_swap(__float_as_uint(pmax), __float_as_uint(pmax), false, false); pmax = fmaxf(__uint_as_float(rr[0]), __uint_as_float(rr[1])); }
;         const bool defer = __all((pmax - m_reg) * SCALE <= THR);
;         const float mn = defer ? m_reg : fmaxf(m_reg, pmax);
;         alpha = __builtin_amdgcn_exp2f((m_reg - mn) * C2); m_reg = mn; mnL = fmaf(-mn, C2, msk); }
;     else if constexpr (k < 9) { constexpr int j = 4 * (k - 5);
; #pragma unroll
;         for (int e = 0; e < 4; ++e) { p0[j + e] = fmaf(p0[j + e], C2, mnL); p1[j + e] = fmaf(p1[j + e], C2, mnL); } }
;     else if constexpr (k < 15) { constexpr int j = 2 * (k - 9); p0[j] = __builtin_amdgcn_exp2f(p0[j]); p0[j + 1] = __builtin_amdgcn_exp2f(p0[j + 1]); }
;     else if constexpr (k == 15) {
; #pragma unroll
;         for (int e = 12; e < 16; ++e) p0[e] = __builtin_amdgcn_exp2f(p0[e]); }
; }
; __device__ __forceinline__ void stage_pv_par(f32x16* o, int vb0, bf16x8 pa0, bf16x8 pa1, bf16x8 pa2, bf16x8 pa3,
;                                              f32x16& x0, f32x16& x1, float& m_reg, float& alpha, float msk) {
;     ...
;     float pmax = 0.f, mnL = 0.f; s16x4 fA[8];
;     SBAR(); PV_RD(fA, 0); PV_WAIT(fA, 0); SBAR();
;     PVS(fA, 0); PV_RD(fA, 1); PV_WAIT(fA, 0); SBAR();
;     PVS(fA, 1); PV_RD(fA, 2); PV_WAIT(fA, 0); SBAR();
;     PVS(fA, 2); PV_RD(fA, 3); PV_WAIT(fA, 0); SBAR();
;     PVS(fA, 3);
;     ...
; }
.Lmy_mid_a:
	s_setprio 0
	s_and_b32 s34, s85, 0xc000
	v_add_u32_e32 v217, s34, v225
	ds_read_b64_tr_b16 v[194:195], v217 offset:0
	ds_read_b64_tr_b16 v[196:197], v217 offset:0x800
	ds_read_b64_tr_b16 v[200:201], v217 offset:0x1000
	ds_read_b64_tr_b16 v[202:203], v217 offset:0x1800
	ds_read_b64_tr_b16 v[204:205], v217 offset:0x2000
	ds_read_b64_tr_b16 v[206:207], v217 offset:0x2800
	ds_read_b64_tr_b16 v[208:209], v217 offset:0x3000
	ds_read_b64_tr_b16 v[210:211], v217 offset:0x3800
	s_nop 0
	s_waitcnt lgkmcnt(0)
	s_nop 0
	v_mfma_f32_32x32x16_bf16 v[64:79], v[194:197], v[2:5], v[64:79]
	s_nop 5
	v_max3_f32 v0, v96, v97, v98
	v_max3_f32 v194, v112, v113, v114
	v_max3_f32 v0, v0, v99, v100
	v_max3_f32 v194, v194, v115, v116
	v_mfma_f32_32x32x16_bf16 v[64:79], v[200:203], v[6:9], v[64:79]
	v_max3_f32 v0, v0, v101, v102
	v_max3_f32 v194, v194, v117, v118
	v_max3_f32 v0, v0, v103, v104
	v_max3_f32 v194, v194, v119, v120
	v_mfma_f32_32x32x16_bf16 v[64:79], v[204:207], v[10:13], v[64:79]
	v_max3_f32 v0, v0, v105, v106
	v_max3_f32 v194, v194, v121, v122
	v_max3_f32 v0, v0, v107, v108
	v_max3_f32 v194, v194, v123, v124
	v_mfma_f32_32x32x16_bf16 v[64:79], v[208:211], v[176:179], v[64:79]
	v_max3_f32 v0, v0, v109, v110
	v_max3_f32 v194, v194, v125, v126
	v_max3_f32 v0, v0, v111, v127
	v_max_f32_e32 v0, v0, v194
	ds_read_b64_tr_b16 v[194:195], v217 offset:0x200
	ds_read_b64_tr_b16 v[196:197], v217 offset:0xa00
	ds_read_b64_tr_b16 v[200:201], v217 offset:0x1200
	ds_read_b64_tr_b16 v[202:203], v217 offset:0x1a00
	ds_read_b64_tr_b16 v[204:205], v217 offset:0x2200
	ds_read_b64_tr_b16 v[206:207], v217 offset:0x2a00
	ds_read_b64_tr_b16 v[208:209], v217 offset:0x3200
	ds_read_b64_tr_b16 v[210:211], v217 offset:0x3a00
	s_nop 0
	s_waitcnt lgkmcnt(0)
	v_add_f32_e32 v0, v216, v0
	v_mfma_f32_32x32x16_bf16 v[48:63], v[194:197], v[2:5], v[48:63]
	v_mov_b32_e32 v194, v0
	s_nop 1
	v_permlane32_swap_b32_e32 v0, v194
	v_max_f32_e32 v0, v0, v194
	v_sub_f32_e32 v194, v0, v244
	v_mul_f32_e32 v194, 0x3d93cd3a, v194
	v_cmp_ge_f32_e32 vcc, s63, v194
	s_cmp_eq_u64 vcc, exec
	s_cselect_b64 vcc, -1, 0
	v_max_f32_e32 v0, v244, v0
	v_cndmask_b32_e32 v246, v0, v244, vcc
	v_sub_f32_e32 v0, v244, v246
	v_mul_f32_e32 v0, 0x3dd53b94, v0
	v_exp_f32_e32 v0, v0
	v_fmac_f32_e32 v216, 0xbdd53b94, v246
	v_mfma_f32_32x32x16_bf16 v[48:63], v[200:203], v[6:9], v[48:63]
	v_fmamk_f32 v96, v96, 0x3dd53b94, v216
	v_fmamk_f32 v97, v97, 0x3dd53b94, v216
	v_fmamk_f32 v98, v98, 0x3dd53b94, v216
	v_fmamk_f32 v99, v99, 0x3dd53b94, v216
	v_exp_f32_e32 v243, v96
	v_mfma_f32_32x32x16_bf16 v[48:63], v[204:207], v[10:13], v[48:63]
	v_fmamk_f32 v100, v100, 0x3dd53b94, v216
	v_fmamk_f32 v101, v101, 0x3dd53b94, v216
	v_exp_f32_e32 v242, v97
	v_exp_f32_e32 v241, v98
	v_mfma_f32_32x32x16_bf16 v[48:63], v[208:211], v[176:179], v[48:63]
	v_fmamk_f32 v102, v102, 0x3dd53b94, v216
	v_fmamk_f32 v103, v103, 0x3dd53b94, v216
	v_exp_f32_e32 v240, v99
	v_exp_f32_e32 v239, v100
	ds_read_b64_tr_b16 v[194:195], v217 offset:0x400
	ds_read_b64_tr_b16 v[196:197], v217 offset:0xc00
	ds_read_b64_tr_b16 v[200:201], v217 offset:0x1400
	ds_read_b64_tr_b16 v[202:203], v217 offset:0x1c00
	ds_read_b64_tr_b16 v[204:205], v217 offset:0x2400
	ds_read_b64_tr_b16 v[206:207], v217 offset:0x2c00
	ds_read_b64_tr_b16 v[208:209], v217 offset:0x3400
	ds_read_b64_tr_b16 v[210:211], v217 offset:0x3c00
	s_nop 0
	s_waitcnt lgkmcnt(0)
	s_nop 0
	v_mfma_f32_32x32x16_bf16 v[32:47], v[194:197], v[2:5], v[32:47]
	v_fmamk_f32 v104, v104, 0x3dd53b94, v216
	v_fmamk_f32 v105, v105, 0x3dd53b94, v216
	v_exp_f32_e32 v238, v101
	v_exp_f32_e32 v237, v102
	v_mfma_f32_32x32x16_bf16 v[32:47], v[200:203], v[6:9], v[32:47]
	v_fmamk_f32 v106, v106, 0x3dd53b94, v216
	v_fmamk_f32 v107, v107, 0x3dd53b94, v216
	v_exp_f32_e32 v236, v103
	v_exp_f32_e32 v235, v104
	v_mfma_f32_32x32x16_bf16 v[32:47], v[204:207], v[10:13], v[32:47]
	v_fmamk_f32 v108, v108, 0x3dd53b94, v216
	v_fmamk_f32 v109, v109, 0x3dd53b94, v216
	v_exp_f32_e32 v234, v105
	v_exp_f32_e32 v233, v106
	v_mfma_f32_32x32x16_bf16 v[32:47], v[208:211], v[176:179], v[32:47]
	v_fmamk_f32 v110, v110, 0x3dd53b94, v216
	v_fmamk_f32 v111, v111, 0x3dd53b94, v216
	v_exp_f32_e32 v232, v107
	v_exp_f32_e32 v231, v108
	ds_read_b64_tr_b16 v[194:195], v217 offset:0x600
	ds_read_b64_tr_b16 v[196:197], v217 offset:0xe00
	ds_read_b64_tr_b16 v[200:201], v217 offset:0x1600
	ds_read_b64_tr_b16 v[202:203], v217 offset:0x1e00
	ds_read_b64_tr_b16 v[204:205], v217 offset:0x2600
	ds_read_b64_tr_b16 v[206:207], v217 offset:0x2e00
	ds_read_b64_tr_b16 v[208:209], v217 offset:0x3600
	ds_read_b64_tr_b16 v[210:211], v217 offset:0x3e00
	s_nop 0
	s_waitcnt lgkmcnt(0)
	s_nop 0
	v_mfma_f32_32x32x16_bf16 v[16:31], v[194:197], v[2:5], v[16:31]
	v_exp_f32_e32 v230, v109
	v_fmamk_f32 v14, v112, 0x3dd53b94, v216
	v_fmamk_f32 v15, v113, 0x3dd53b94, v216
	v_fmamk_f32 v116, v116, 0x3dd53b94, v216
	v_fmamk_f32 v117, v117, 0x3dd53b94, v216
	v_mfma_f32_32x32x16_bf16 v[16:31], v[200:203], v[6:9], v[16:31]
	v_fmamk_f32 v118, v118, 0x3dd53b94, v216
	v_fmamk_f32 v119, v119, 0x3dd53b94, v216
	v_fmamk_f32 v120, v120, 0x3dd53b94, v216
	v_fmamk_f32 v121, v121, 0x3dd53b94, v216
	v_fmamk_f32 v122, v122, 0x3dd53b94, v216
	v_fmamk_f32 v123, v123, 0x3dd53b94, v216
	v_mfma_f32_32x32x16_bf16 v[16:31], v[204:207], v[10:13], v[16:31]
	v_fmamk_f32 v124, v124, 0x3dd53b94, v216
	v_fmamk_f32 v125, v125, 0x3dd53b94, v216
	v_fmamk_f32 v126, v126, 0x3dd53b94, v216
	v_fmamk_f32 v127, v127, 0x3dd53b94, v216
	v_mfma_f32_32x32x16_bf16 v[16:31], v[208:211], v[176:179], v[16:31]
	v_cmp_gt_f32_e32 vcc, 1.0, v0
	s_cbranch_vccz .LBB0_330
	v_pk_mul_f32 v[78:79], v[78:79], v[0:1] op_sel_hi:[1,0]
	v_pk_mul_f32 v[76:77], v[76:77], v[0:1] op_sel_hi:[1,0]
	v_pk_mul_f32 v[74:75], v[74:75], v[0:1] op_sel_hi:[1,0]
	v_pk_mul_f32 v[72:73], v[72:73], v[0:1] op_sel_hi:[1,0]
	v_pk_mul_f32 v[70:71], v[70:71], v[0:1] op_sel_hi:[1,0]
	v_pk_mul_f32 v[68:69], v[68:69], v[0:1] op_sel_hi:[1,0]
	v_pk_mul_f32 v[66:67], v[66:67], v[0:1] op_sel_hi:[1,0]
	v_pk_mul_f32 v[64:65], v[64:65], v[0:1] op_sel_hi:[1,0]
	v_pk_mul_f32 v[62:63], v[0:1], v[62:63] op_sel_hi:[0,1]
	v_pk_mul_f32 v[60:61], v[0:1], v[60:61] op_sel_hi:[0,1]
	v_pk_mul_f32 v[58:59], v[0:1], v[58:59] op_sel_hi:[0,1]
	v_pk_mul_f32 v[56:57], v[0:1], v[56:57] op_sel_hi:[0,1]
	v_pk_mul_f32 v[54:55], v[0:1], v[54:55] op_sel_hi:[0,1]
	v_pk_mul_f32 v[52:53], v[0:1], v[52:53] op_sel_hi:[0,1]
	v_pk_mul_f32 v[50:51], v[0:1], v[50:51] op_sel_hi:[0,1]
	v_pk_mul_f32 v[48:49], v[0:1], v[48:49] op_sel_hi:[0,1]
	v_pk_mul_f32 v[46:47], v[0:1], v[46:47] op_sel_hi:[0,1]
	v_pk_mul_f32 v[44:45], v[0:1], v[44:45] op_sel_hi:[0,1]
	v_pk_mul_f32 v[42:43], v[0:1], v[42:43] op_sel_hi:[0,1]
	v_pk_mul_f32 v[40:41], v[0:1], v[40:41] op_sel_hi:[0,1]
	v_pk_mul_f32 v[38:39], v[0:1], v[38:39] op_sel_hi:[0,1]
	v_pk_mul_f32 v[36:37], v[0:1], v[36:37] op_sel_hi:[0,1]
	v_pk_mul_f32 v[34:35], v[0:1], v[34:35] op_sel_hi:[0,1]
	v_pk_mul_f32 v[32:33], v[0:1], v[32:33] op_sel_hi:[0,1]
	v_pk_mul_f32 v[30:31], v[0:1], v[30:31] op_sel_hi:[0,1]
	v_pk_mul_f32 v[28:29], v[0:1], v[28:29] op_sel_hi:[0,1]
	v_pk_mul_f32 v[26:27], v[0:1], v[26:27] op_sel_hi:[0,1]
	v_pk_mul_f32 v[24:25], v[0:1], v[24:25] op_sel_hi:[0,1]
	v_pk_mul_f32 v[22:23], v[0:1], v[22:23] op_sel_hi:[0,1]
	v_pk_mul_f32 v[20:21], v[0:1], v[20:21] op_sel_hi:[0,1]
	v_pk_mul_f32 v[18:19], v[0:1], v[18:19] op_sel_hi:[0,1]
	v_pk_mul_f32 v[16:17], v[0:1], v[16:17] op_sel_hi:[0,1]

; template <int k> __device__ __forceinline__ void fin_snip(f32x16& p0, f32x16& p1, float alpha, float& l_reg, float& ps, bf16x8& pa0, bf16x8& pa1, bf16x8& pa2, bf16x8& pa3) {
;     if constexpr (k < 8) { p1[2 * k] = __builtin_amdgcn_exp2f(p1[2 * k]); p1[2 * k + 1] = __builtin_amdgcn_exp2f(p1[2 * k + 1]); }
;     else if constexpr (k < 16) { constexpr int j = 2 * (k - 8); const float a = (p0[j] + p0[j + 1]) + (p1[j] + p1[j + 1]); ps = (k == 8) ? a : ps + a; }
;     else if constexpr (k == 16) { auto rr = __builtin_amdgcn_permlane32_swap(__float_as_uint(ps), __float_as_uint(ps), false, false);
;         ps = __uint_as_float(rr[0]) + __uint_as_float(rr[1]); l_reg = l_reg * alpha + ps; }
;     else if constexpr (k == 17) { PK4(p0, 0, pa0); }
;     else if constexpr (k == 18) { PK4(p0, 8, pa1); }
;     else if constexpr (k == 19) { PK4(p1, 0, pa2); }
;     else if constexpr (k == 20) { PK4(p1, 8, pa3); }
; }
; template <int k> __device__ __forceinline__ void par_snip(f32x16& p0, f32x16& p1, float& m_reg, float& pmax, float& alpha, float& mnL, float msk) {
;     constexpr float C2 = 1.4426950408889634f * SCALE;
;     if constexpr (k < 4) { constexpr int j = 4 * k; const float a = fmaxf(fmaxf(p0[j], p0[j + 1]), fmaxf(p0[j + 2], p0[j + 3])), b = fmaxf(fmaxf(p1[j], p1[j + 1]), fmaxf(p1[j + 2], p1[j + 3]));
;         pmax = (k == 0) ? fmaxf(a, b) : fmaxf(pmax, fmaxf(a, b)); }
;     else if constexpr (k == 4) { pmax += msk;
;         { auto rr = __builtin_amdgcn_permlane32_swap(__float_as_uint(pmax), __float_as_uint(pmax), false, false); pmax = fmaxf(__uint_as_float(rr[0]), __uint_as_float(rr[1])); }
;         const bool defer = __all((pmax - m_reg) * SCALE <= THR);
;         const float mn = defer ? m_reg : fmaxf(m_reg, pmax);
;         alpha = __builtin_amdgcn_exp2f((m_reg - mn) * C2); m_reg = mn; mnL = fmaf(-mn, C2, msk); }
;     else if constexpr (k < 9) { constexpr int j = 4 * (k - 5);
; #pragma unroll
;         for (int e = 0; e < 4; ++e) { p0[j + e] = fmaf(p0[j + e], C2, mnL); p1[j + e] = fmaf(p1[j + e], C2, mnL); } }
;     else if constexpr (k < 15) { constexpr int j = 2 * (k - 9); p0[j] = __builtin_amdgcn_exp2f(p0[j]); p0[j + 1] = __builtin_amdgcn_exp2f(p0[j + 1]); }
;     else if constexpr (k == 15) {
; #pragma unroll
;         for (int e = 12; e < 16; ++e) p0[e] = __builtin_amdgcn_exp2f(p0[e]); }
; }
.LBB0_333:
	s_setprio 1
	s_add_i32 s34, s85, 0xffff4000
	s_cmp_lt_i32 s86, s84
	s_cselect_b64 s[86:87], -1, 0
	v_cndmask_b32_e64 v178, v223, 0, s[86:87]
	ds_read_b128 v[2:5], v181 offset:0
	ds_read_b128 v[6:9], v181 offset:0x3000
	ds_read_b128 v[10:13], v219 offset:0
	ds_read_b128 v[112:115], v219 offset:0x3000
	s_nop 0
	s_waitcnt lgkmcnt(2)
	s_nop 0
	v_mfma_f32_32x32x16_bf16 v[96:111], v[2:5], v[128:131], 0
	v_exp_f32_e32 v14, v14
	v_exp_f32_e32 v15, v15
	v_mfma_f32_32x32x16_bf16 v[80:95], v[6:9], v[128:131], 0
	v_exp_f32_e32 v176, v176
	v_exp_f32_e32 v177, v177
	ds_read_b128 v[2:5], v220 offset:0
	ds_read_b128 v[6:9], v220 offset:0x3000
	s_waitcnt lgkmcnt(2)
	s_nop 0
	v_mfma_f32_32x32x16_bf16 v[96:111], v[10:13], v[132:135], v[96:111]
	v_exp_f32_e32 v116, v116
	v_exp_f32_e32 v117, v117
	v_mfma_f32_32x32x16_bf16 v[80:95], v[112:115], v[132:135], v[80:95]
	v_exp_f32_e32 v118, v118
	v_exp_f32_e32 v119, v119
	ds_read_b128 v[10:13], v221 offset:0
	ds_read_b128 v[112:115], v221 offset:0x3000
	s_waitcnt lgkmcnt(2)
	s_nop 0
	v_mfma_f32_32x32x16_bf16 v[96:111], v[2:5], v[136:139], v[96:111]
	v_exp_f32_e32 v120, v120
	v_exp_f32_e32 v121, v121
	v_mfma_f32_32x32x16_bf16 v[80:95], v[6:9], v[136:139], v[80:95]
	v_exp_f32_e32 v122, v122
	v_exp_f32_e32 v123, v123
	ds_read_b128 v[2:5], v181 offset:0x80
	ds_read_b128 v[6:9], v181 offset:0x3080
	s_waitcnt lgkmcnt(2)
	s_nop 0
	v_mfma_f32_32x32x16_bf16 v[96:111], v[10:13], v[140:143], v[96:111]
	v_exp_f32_e32 v124, v124
	v_exp_f32_e32 v125, v125
	v_mfma_f32_32x32x16_bf16 v[80:95], v[112:115], v[140:143], v[80:95]
	v_exp_f32_e32 v126, v126
	v_exp_f32_e32 v127, v127
	ds_read_b128 v[10:13], v219 offset:0x80
	ds_read_b128 v[112:115], v219 offset:0x3080
	s_waitcnt lgkmcnt(2)
	s_nop 0
	v_mfma_f32_32x32x16_bf16 v[96:111], v[2:5], v[144:147], v[96:111]
	v_add_f32_e32 v2, v243, v242
	v_add_f32_e32 v3, v14, v15
	v_add_f32_e32 v2, v2, v3
	v_mfma_f32_32x32x16_bf16 v[80:95], v[6:9], v[144:147], v[80:95]
	v_add_f32_e32 v3, v241, v240
	v_add_f32_e32 v4, v176, v177
	v_add_f32_e32 v3, v3, v4
	v_add_f32_e32 v192, v2, v3
	ds_read_b128 v[2:5], v220 offset:0x80
	ds_read_b128 v[6:9], v220 offset:0x3080
	s_waitcnt lgkmcnt(2)
	s_nop 0
	v_mfma_f32_32x32x16_bf16 v[96:111], v[10:13], v[148:151], v[96:111]
	v_add_f32_e32 v10, v239, v238
	v_add_f32_e32 v11, v116, v117
	v_add_f32_e32 v10, v10, v11
	v_add_f32_e32 v10, v10, v192
	v_mfma_f32_32x32x16_bf16 v[80:95], v[112:115], v[148:151], v[80:95]
	v_add_f32_e32 v11, v237, v236
	v_add_f32_e32 v12, v118, v119
	v_add_f32_e32 v11, v11, v12
	v_add_f32_e32 v192, v11, v10
	ds_read_b128 v[10:13], v221 offset:0x80
	ds_read_b128 v[112:115], v221 offset:0x3080
	s_waitcnt lgkmcnt(2)
	s_nop 0
	v_mfma_f32_32x32x16_bf16 v[96:111], v[2:5], v[152:155], v[96:111]
	v_add_f32_e32 v2, v235, v234
	v_add_f32_e32 v3, v120, v121
	v_add_f32_e32 v2, v2, v3
	v_add_f32_e32 v2, v2, v192
	v_mfma_f32_32x32x16_bf16 v[80:95], v[6:9], v[152:155], v[80:95]
	v_add_f32_e32 v3, v233, v232
	v_add_f32_e32 v4, v122, v123
	v_add_f32_e32 v3, v3, v4
	v_add_f32_e32 v192, v3, v2
	ds_read_b128 v[2:5], v181 offset:0x100
	ds_read_b128 v[6:9], v181 offset:0x3100
	s_waitcnt lgkmcnt(2)
	s_nop 0
	v_mfma_f32_32x32x16_bf16 v[96:111], v[10:13], v[156:159], v[96:111]
	v_add_f32_e32 v10, v231, v230
	v_add_f32_e32 v11, v124, v125
	v_add_f32_e32 v10, v10, v11
	v_add_f32_e32 v10, v10, v192
	v_mfma_f32_32x32x16_bf16 v[80:95], v[112:115], v[156:159], v[80:95]
	v_add_f32_e32 v11, v216, v179
	v_add_f32_e32 v12, v126, v127
	v_add_f32_e32 v11, v11, v12
	v_add_f32_e32 v200, v11, v10
	ds_read_b128 v[10:13], v219 offset:0x100
	ds_read_b128 v[112:115], v219 offset:0x3100
	s_waitcnt lgkmcnt(2)
	s_nop 0
	v_mfma_f32_32x32x16_bf16 v[96:111], v[2:5], v[160:163], v[96:111]
	v_mov_b32_e32 v201, v200
	s_nop 1
	v_permlane32_swap_b32_e32 v200, v201
	v_mfma_f32_32x32x16_bf16 v[80:95], v[6:9], v[160:163], v[80:95]
	v_cvt_pk_bf16_f32 v2, v243, v242
	v_cvt_pk_bf16_f32 v3, v241, v240
	v_cvt_pk_bf16_f32 v4, v239, v238
	v_cvt_pk_bf16_f32 v5, v237, v236
	ds_read_b128 v[194:197], v220 offset:0x100
	ds_read_b128 v[202:205], v220 offset:0x3100
	s_waitcnt lgkmcnt(2)
	s_nop 0
	v_mfma_f32_32x32x16_bf16 v[96:111], v[10:13], v[164:167], v[96:111]
	v_cvt_pk_bf16_f32 v6, v235, v234
	v_cvt_pk_bf16_f32 v7, v233, v232
	v_cvt_pk_bf16_f32 v8, v231, v230
	v_cvt_pk_bf16_f32 v9, v216, v179
	v_mfma_f32_32x32x16_bf16 v[80:95], v[112:115], v[164:167], v[80:95]
	v_cvt_pk_bf16_f32 v10, v14, v15
	v_cvt_pk_bf16_f32 v11, v176, v177
	v_cvt_pk_bf16_f32 v12, v116, v117
	v_cvt_pk_bf16_f32 v13, v118, v119
	ds_read_b128 v[206:209], v221 offset:0x100
	ds_read_b128 v[210:213], v221 offset:0x3100
	s_waitcnt lgkmcnt(2)
	s_nop 0
	v_mfma_f32_32x32x16_bf16 v[96:111], v[194:197], v[168:171], v[96:111]
	v_cvt_pk_bf16_f32 v112, v120, v121
	v_cvt_pk_bf16_f32 v113, v122, v123
	v_cvt_pk_bf16_f32 v114, v124, v125
	v_cvt_pk_bf16_f32 v115, v126, v127
	v_mfma_f32_32x32x16_bf16 v[80:95], v[202:205], v[168:171], v[80:95]
	v_add_f32_e32 v247, v200, v201
	v_fma_f32 v245, v245, v0, v247
	s_waitcnt lgkmcnt(0)
	s_nop 0
	v_mfma_f32_32x32x16_bf16 v[96:111], v[206:209], v[172:175], v[96:111]
	v_mfma_f32_32x32x16_bf16 v[80:95], v[210:213], v[172:175], v[80:95]
	s_cmp_eq_u32 s100, 0
	s_cbranch_scc1 .Lmy_mid_b
	s_waitcnt vmcnt(0)
	s_barrier
; #define SBAR() __builtin_amdgcn_sched_barrier(0)
; #define PV_RD(F_, d0) do { constexpr int b_ = V_OFF + v_rd_off(d0, 0, 0); \
;         TRRD(F_[0], b_); TRRD(F_[1], b_ + 2048); TRRD(F_[2], b_ + 4096); TRRD(F_[3], b_ + 6144); TRRD(F_[4], b_ + 8192); TRRD(F_[5], b_ + 10240); TRRD(F_[6], b_ + 12288); TRRD(F_[7], b_ + 14336); } while (0)
; template <int k> __device__ __forceinline__ void par_snip(f32x16& p0, f32x16& p1, float& m_reg, float& pmax, float& alpha, float& mnL, float msk) {
;     constexpr float C2 = 1.4426950408889634f * SCALE;
;     if constexpr (k < 4) { constexpr int j = 4 * k; const float a = fmaxf(fmaxf(p0[j], p0[j + 1]), fmaxf(p0[j + 2], p0[j + 3])), b = fmaxf(fmaxf(p1[j], p1[j + 1]), fmaxf(p1[j + 2], p1[j + 3]));
;         pmax = (k == 0) ? fmaxf(a, b) : fmaxf(pmax, fmaxf(a, b)); }
;     else if constexpr (k == 4) { pmax += msk;
;         { auto rr = __builtin_amdgcn_permlane32_swap(__float_as_uint(pmax), __float_as_uint(pmax), false, false); pmax = fmaxf(__uint_as_float(rr[0]), __uint_as_float(rr[1])); }
;         const bool defer = __all((pmax - m_reg) * SCALE <= THR);
;         const float mn = defer ? m_reg : fmaxf(m_reg, pmax);
;         alpha = __builtin_amdgcn_exp2f((m_reg - mn) * C2); m_reg = mn; mnL = fmaf(-mn, C2, msk); }
;     else if constexpr (k < 9) { constexpr int j = 4 * (k - 5);
; #pragma unroll
;         for (int e = 0; e < 4; ++e) { p0[j + e] = fmaf(p0[j + e], C2, mnL); p1[j + e] = fmaf(p1[j + e], C2, mnL); } }
;     else if constexpr (k < 15) { constexpr int j = 2 * (k - 9); p0[j] = __builtin_amdgcn_exp2f(p0[j]); p0[j + 1] = __builtin_amdgcn_exp2f(p0[j + 1]); }
;     else if constexpr (k == 15) {
; #pragma unroll
;         for (int e = 12; e < 16; ++e) p0[e] = __builtin_amdgcn_exp2f(p0[e]); }
; }
; __device__ __forceinline__ void stage_pv_par(f32x16* o, int vb0, bf16x8 pa0, bf16x8 pa1, bf16x8 pa2, bf16x8 pa3,
;                                              f32x16& x0, f32x16& x1, float& m_reg, float& alpha, float msk) {
;     ...
;     float pmax = 0.f, mnL = 0.f; s16x4 fA[8];
;     SBAR(); PV_RD(fA, 0); PV_WAIT(fA, 0); SBAR();
;     PVS(fA, 0); PV_RD(fA, 1); PV_WAIT(fA, 0); SBAR();
;     PVS(fA, 1); PV_RD(fA, 2); PV_WAIT(fA, 0); SBAR();
;     PVS(fA, 2); PV_RD(fA, 3); PV_WAIT(fA, 0); SBAR();
;     PVS(fA, 3);
;     ...
; }
.Lmy_mid_b:
	s_setprio 0
	s_and_b32 s34, s34, 0xc000
	v_add_u32_e32 v217, s34, v225
	ds_read_b64_tr_b16 v[194:195], v217 offset:0
	ds_read_b64_tr_b16 v[196:197], v217 offset:0x800
	ds_read_b64_tr_b16 v[232:233], v217 offset:0x1000
	ds_read_b64_tr_b16 v[234:235], v217 offset:0x1800
	ds_read_b64_tr_b16 v[236:237], v217 offset:0x2000
	ds_read_b64_tr_b16 v[238:239], v217 offset:0x2800
	ds_read_b64_tr_b16 v[240:241], v217 offset:0x3000
	ds_read_b64_tr_b16 v[242:243], v217 offset:0x3800
	s_nop 0
	s_waitcnt lgkmcnt(0)
	s_nop 0
	v_mfma_f32_32x32x16_bf16 v[64:79], v[194:197], v[2:5], v[64:79]
	s_nop 5
	v_max3_f32 v192, v96, v97, v98
	v_max3_f32 v194, v80, v81, v82
	v_max3_f32 v192, v192, v99, v100
	v_max3_f32 v194, v194, v83, v84
	v_mfma_f32_32x32x16_bf16 v[64:79], v[232:235], v[6:9], v[64:79]
	v_max3_f32 v192, v192, v101, v102
	v_max3_f32 v194, v194, v85, v86
	v_max3_f32 v192, v192, v103, v104
	v_max3_f32 v194, v194, v87, v88
	v_mfma_f32_32x32x16_bf16 v[64:79], v[236:239], v[10:13], v[64:79]
	v_max3_f32 v192, v192, v105, v106
	v_max3_f32 v194, v194, v89, v90
	v_max3_f32 v192, v192, v107, v108
	v_max3_f32 v194, v194, v91, v92
	v_mfma_f32_32x32x16_bf16 v[64:79], v[240:243], v[112:115], v[64:79]
	v_max3_f32 v192, v192, v109, v110
	v_max3_f32 v194, v194, v93, v94
	v_max3_f32 v192, v192, v111, v95
	v_max_f32_e32 v192, v192, v194
	ds_read_b64_tr_b16 v[194:195], v217 offset:0x200
	ds_read_b64_tr_b16 v[196:197], v217 offset:0xa00
	ds_read_b64_tr_b16 v[232:233], v217 offset:0x1200
	ds_read_b64_tr_b16 v[234:235], v217 offset:0x1a00
	ds_read_b64_tr_b16 v[236:237], v217 offset:0x2200
	ds_read_b64_tr_b16 v[238:239], v217 offset:0x2a00
	ds_read_b64_tr_b16 v[240:241], v217 offset:0x3200
	ds_read_b64_tr_b16 v[242:243], v217 offset:0x3a00
	s_nop 0
	s_waitcnt lgkmcnt(0)
	v_add_f32_e32 v192, v178, v192
	v_mfma_f32_32x32x16_bf16 v[48:63], v[194:197], v[2:5], v[48:63]
	v_mov_b32_e32 v194, v192
	s_nop 1
	v_permlane32_swap_b32_e32 v192, v194
	v_max_f32_e32 v192, v192, v194
	v_sub_f32_e32 v194, v192, v246
	v_mul_f32_e32 v194, 0x3d93cd3a, v194
	v_cmp_ge_f32_e32 vcc, s63, v194
	s_cmp_eq_u64 vcc, exec
	s_cselect_b64 vcc, -1, 0
	v_max_f32_e32 v192, v246, v192
	v_cndmask_b32_e32 v244, v192, v246, vcc
	v_sub_f32_e32 v192, v246, v244
	v_mul_f32_e32 v192, 0x3dd53b94, v192
	v_exp_f32_e32 v192, v192
	v_fmac_f32_e32 v178, 0xbdd53b94, v244
	v_mfma_f32_32x32x16_bf16 v[48:63], v[232:235], v[6:9], v[48:63]
	v_fmamk_f32 v214, v80, 0x3dd53b94, v178
	v_fmamk_f32 v215, v81, 0x3dd53b94, v178
	v_fmamk_f32 v212, v82, 0x3dd53b94, v178
	v_fmamk_f32 v213, v83, 0x3dd53b94, v178
	v_fmamk_f32 v210, v84, 0x3dd53b94, v178
	v_fmamk_f32 v211, v85, 0x3dd53b94, v178
	v_mfma_f32_32x32x16_bf16 v[48:63], v[236:239], v[10:13], v[48:63]
	v_fmamk_f32 v208, v86, 0x3dd53b94, v178
	v_fmamk_f32 v209, v87, 0x3dd53b94, v178
	v_fmamk_f32 v206, v88, 0x3dd53b94, v178
	v_fmamk_f32 v207, v89, 0x3dd53b94, v178
	v_fmamk_f32 v204, v90, 0x3dd53b94, v178
	v_fmamk_f32 v205, v91, 0x3dd53b94, v178
	v_mfma_f32_32x32x16_bf16 v[48:63], v[240:243], v[112:115], v[48:63]
	v_fmamk_f32 v202, v92, 0x3dd53b94, v178
	v_fmamk_f32 v203, v93, 0x3dd53b94, v178
	v_fmamk_f32 v200, v94, 0x3dd53b94, v178
	v_fmamk_f32 v201, v95, 0x3dd53b94, v178
	v_fmamk_f32 v96, v96, 0x3dd53b94, v178
	v_fmamk_f32 v97, v97, 0x3dd53b94, v178
	ds_read_b64_tr_b16 v[194:195], v217 offset:0x400
	ds_read_b64_tr_b16 v[196:197], v217 offset:0xc00
	ds_read_b64_tr_b16 v[232:233], v217 offset:0x1400
	ds_read_b64_tr_b16 v[234:235], v217 offset:0x1c00
	ds_read_b64_tr_b16 v[236:237], v217 offset:0x2400
	ds_read_b64_tr_b16 v[238:239], v217 offset:0x2c00
	ds_read_b64_tr_b16 v[240:241], v217 offset:0x3400
	ds_read_b64_tr_b16 v[242:243], v217 offset:0x3c00
	s_nop 0
	s_waitcnt lgkmcnt(0)
	s_nop 0
	v_mfma_f32_32x32x16_bf16 v[32:47], v[194:197], v[2:5], v[32:47]
	v_fmamk_f32 v98, v98, 0x3dd53b94, v178
	v_fmamk_f32 v99, v99, 0x3dd53b94, v178
	v_exp_f32_e32 v80, v96
	v_exp_f32_e32 v81, v97
	v_mfma_f32_32x32x16_bf16 v[32:47], v[232:235], v[6:9], v[32:47]
	v_fmamk_f32 v100, v100, 0x3dd53b94, v178
	v_fmamk_f32 v101, v101, 0x3dd53b94, v178
	v_exp_f32_e32 v82, v98
	v_exp_f32_e32 v83, v99
	v_mfma_f32_32x32x16_bf16 v[32:47], v[236:239], v[10:13], v[32:47]
	v_fmamk_f32 v102, v102, 0x3dd53b94, v178
	v_fmamk_f32 v103, v103, 0x3dd53b94, v178
	v_exp_f32_e32 v84, v100
	v_exp_f32_e32 v85, v101
	v_mfma_f32_32x32x16_bf16 v[32:47], v[240:243], v[112:115], v[32:47]
	v_fmamk_f32 v104, v104, 0x3dd53b94, v178
	v_fmamk_f32 v105, v105, 0x3dd53b94, v178
	v_exp_f32_e32 v86, v102
	v_exp_f32_e32 v87, v103
	ds_read_b64_tr_b16 v[194:195], v217 offset:0x600
	ds_read_b64_tr_b16 v[196:197], v217 offset:0xe00
	ds_read_b64_tr_b16 v[232:233], v217 offset:0x1600
	ds_read_b64_tr_b16 v[234:235], v217 offset:0x1e00
	ds_read_b64_tr_b16 v[236:237], v217 offset:0x2600
	ds_read_b64_tr_b16 v[238:239], v217 offset:0x2e00
	ds_read_b64_tr_b16 v[240:241], v217 offset:0x3600
	ds_read_b64_tr_b16 v[242:243], v217 offset:0x3e00
	s_nop 0
	s_waitcnt lgkmcnt(0)
	s_nop 0
	v_mfma_f32_32x32x16_bf16 v[16:31], v[194:197], v[2:5], v[16:31]
	v_fmamk_f32 v106, v106, 0x3dd53b94, v178
	v_fmamk_f32 v107, v107, 0x3dd53b94, v178
	v_exp_f32_e32 v88, v104
	v_exp_f32_e32 v89, v105
	v_mfma_f32_32x32x16_bf16 v[16:31], v[232:235], v[6:9], v[16:31]
	v_fmamk_f32 v108, v108, 0x3dd53b94, v178
	v_fmamk_f32 v109, v109, 0x3dd53b94, v178
	v_exp_f32_e32 v90, v106
	v_exp_f32_e32 v91, v107
	v_mfma_f32_32x32x16_bf16 v[16:31], v[236:239], v[10:13], v[16:31]
	v_fmamk_f32 v110, v110, 0x3dd53b94, v178
	v_fmamk_f32 v111, v111, 0x3dd53b94, v178
	v_exp_f32_e32 v92, v108
	v_exp_f32_e32 v93, v109
	v_mfma_f32_32x32x16_bf16 v[16:31], v[240:243], v[112:115], v[16:31]
	v_cmp_gt_f32_e32 vcc, 1.0, v192
	s_cbranch_vccz .LBB0_335
	v_pk_mul_f32 v[78:79], v[78:79], v[192:193] op_sel_hi:[1,0]
	v_pk_mul_f32 v[76:77], v[76:77], v[192:193] op_sel_hi:[1,0]
	v_pk_mul_f32 v[74:75], v[74:75], v[192:193] op_sel_hi:[1,0]
	v_pk_mul_f32 v[72:73], v[72:73], v[192:193] op_sel_hi:[1,0]
	v_pk_mul_f32 v[70:71], v[70:71], v[192:193] op_sel_hi:[1,0]
	v_pk_mul_f32 v[68:69], v[68:69], v[192:193] op_sel_hi:[1,0]
	v_pk_mul_f32 v[66:67], v[66:67], v[192:193] op_sel_hi:[1,0]
	v_pk_mul_f32 v[64:65], v[64:65], v[192:193] op_sel_hi:[1,0]
	v_pk_mul_f32 v[62:63], v[192:193], v[62:63] op_sel_hi:[0,1]
	v_pk_mul_f32 v[60:61], v[192:193], v[60:61] op_sel_hi:[0,1]
	v_pk_mul_f32 v[58:59], v[192:193], v[58:59] op_sel_hi:[0,1]
	v_pk_mul_f32 v[56:57], v[192:193], v[56:57] op_sel_hi:[0,1]
	v_pk_mul_f32 v[54:55], v[192:193], v[54:55] op_sel_hi:[0,1]
	v_pk_mul_f32 v[52:53], v[192:193], v[52:53] op_sel_hi:[0,1]
	v_pk_mul_f32 v[50:51], v[192:193], v[50:51] op_sel_hi:[0,1]
	v_pk_mul_f32 v[48:49], v[192:193], v[48:49] op_sel_hi:[0,1]
	v_pk_mul_f32 v[46:47], v[192:193], v[46:47] op_sel_hi:[0,1]
	v_pk_mul_f32 v[44:45], v[192:193], v[44:45] op_sel_hi:[0,1]
	v_pk_mul_f32 v[42:43], v[192:193], v[42:43] op_sel_hi:[0,1]
	v_pk_mul_f32 v[40:41], v[192:193], v[40:41] op_sel_hi:[0,1]
	v_pk_mul_f32 v[38:39], v[192:193], v[38:39] op_sel_hi:[0,1]
	v_pk_mul_f32 v[36:37], v[192:193], v[36:37] op_sel_hi:[0,1]
	v_pk_mul_f32 v[34:35], v[192:193], v[34:35] op_sel_hi:[0,1]
	v_pk_mul_f32 v[32:33], v[192:193], v[32:33] op_sel_hi:[0,1]
	v_pk_mul_f32 v[30:31], v[192:193], v[30:31] op_sel_hi:[0,1]
	v_pk_mul_f32 v[28:29], v[192:193], v[28:29] op_sel_hi:[0,1]
	v_pk_mul_f32 v[26:27], v[192:193], v[26:27] op_sel_hi:[0,1]
	v_pk_mul_f32 v[24:25], v[192:193], v[24:25] op_sel_hi:[0,1]
	v_pk_mul_f32 v[22:23], v[192:193], v[22:23] op_sel_hi:[0,1]
	v_pk_mul_f32 v[20:21], v[192:193], v[20:21] op_sel_hi:[0,1]
	v_pk_mul_f32 v[18:19], v[192:193], v[18:19] op_sel_hi:[0,1]
	v_pk_mul_f32 v[16:17], v[192:193], v[16:17] op_sel_hi:[0,1]
